# norm1/norm2 output stores also device-scope (less L2 write-back at the following grid barrier)
# baseline (speedup 1.0000x reference)
; __device__ __forceinline__ void store8bf(bf16_t* p, f32x4 v0, f32x4 v1) { u32x4 w; w.x = cvt_pk_bf16(v0[0], v0[1]); w.y = cvt_pk_bf16(v0[2], v0[3]); w.z = cvt_pk_bf16(v1[0], v1[1]); w.w = cvt_pk_bf16(v1[2], v1[3]); *(u32x4*)p = w; }
; __device__ __forceinline__ void norm_phase(const float* H, const float* g, bf16_t* HN) {
;     ...
;   for (int row = gw; row < NREAL + 64; row += 2 * nw) {
;     const int row2 = row + nw < NREAL + 64 ? row + nw : row;
;     const float* p = H + (size_t)row * DM + lane * 8; const float* p2 = H + (size_t)row2 * DM + lane * 8; f32x4 v[4], u[4]; float ss = 0.f, ss2 = 0.f;
; #pragma unroll
;     for (int i = 0; i < 4; ++i) { v[i] = *(const f32x4*)(p + 512 * (i >> 1) + 4 * (i & 1)); u[i] = *(const f32x4*)(p2 + 512 * (i >> 1) + 4 * (i & 1)); }
; #pragma unroll
;     for (int i = 0; i < 4; ++i) { ss += v[i][0] * v[i][0] + v[i][1] * v[i][1] + v[i][2] * v[i][2] + v[i][3] * v[i][3]; ss2 += u[i][0] * u[i][0] + u[i][1] * u[i][1] + u[i][2] * u[i][2] + u[i][3] * u[i][3]; }
;     ss = wave_sum(ss); ss2 = wave_sum(ss2); const float rs = rsqrtf(ss * (1.0f / 1024.0f) + 1e-6f), rs2 = rsqrtf(ss2 * (1.0f / 1024.0f) + 1e-6f);
;     bf16_t* q = HN + (size_t)row * DM + lane * 8; bf16_t* q2 = HN + (size_t)row2 * DM + lane * 8;
; #pragma unroll
;     for (int i = 0; i < 2; ++i) { store8bf(q + 512 * i, v[2 * i] * rs * gv[2 * i], v[2 * i + 1] * rs * gv[2 * i + 1]); store8bf(q2 + 512 * i, u[2 * i] * rs2 * gv[2 * i], u[2 * i + 1] * rs2 * gv[2 * i + 1]); }
.LBB0_224:
	v_readfirstlane_b32 s0, v22
	s_nop 3
	s_add_i32 s11, s0, s8
	s_cmp_lt_i32 s11, s49
	s_cselect_b32 s11, s11, s0
	s_lshl_b32 s12, s0, 12
	s_lshl_b32 s13, s11, 12
	v_mov_b32_e32 v68, s12
	v_mov_b32_e32 v69, 0
	v_lshl_add_u64 v[64:65], v[18:19], 0, v[68:69]
	v_mov_b32_e32 v68, s13
	v_lshl_add_u64 v[66:67], v[18:19], 0, v[68:69]
	global_load_dwordx4 v[26:29], v[64:65], off
	global_load_dwordx4 v[30:33], v[64:65], off offset:1024
	global_load_dwordx4 v[34:37], v[64:65], off offset:2048
	global_load_dwordx4 v[38:41], v[64:65], off offset:3072
	global_load_dwordx4 v[42:45], v[66:67], off
	global_load_dwordx4 v[46:49], v[66:67], off offset:1024
	global_load_dwordx4 v[50:53], v[66:67], off offset:2048
	global_load_dwordx4 v[54:57], v[66:67], off offset:3072
	s_lshl_b32 s12, s0, 11
	s_lshl_b32 s13, s11, 11
	v_mov_b32_e32 v68, s12
	v_lshl_add_u64 v[24:25], v[20:21], 0, v[68:69]
	v_mov_b32_e32 v68, s13
	v_lshl_add_u64 v[58:59], v[20:21], 0, v[68:69]
	s_lshl_b32 s9, s8, 1
	s_add_i32 s1, s0, s9
	s_cmp_lt_i32 s1, s49
	s_cbranch_scc0 .Ln1_lastA_first
	s_add_i32 s11, s1, s8
	s_cmp_lt_i32 s11, s49
	s_cselect_b32 s11, s11, s1
	s_lshl_b32 s12, s1, 12
	s_lshl_b32 s13, s11, 12
	v_mov_b32_e32 v68, s12
	v_mov_b32_e32 v69, 0
	v_lshl_add_u64 v[64:65], v[18:19], 0, v[68:69]
	v_mov_b32_e32 v68, s13
	v_lshl_add_u64 v[66:67], v[18:19], 0, v[68:69]
	global_load_dwordx4 v[88:91], v[64:65], off
	global_load_dwordx4 v[92:95], v[64:65], off offset:1024
	global_load_dwordx4 v[96:99], v[64:65], off offset:2048
	global_load_dwordx4 v[100:103], v[64:65], off offset:3072
	global_load_dwordx4 v[128:131], v[66:67], off
	global_load_dwordx4 v[132:135], v[66:67], off offset:1024
	global_load_dwordx4 v[136:139], v[66:67], off offset:2048
	global_load_dwordx4 v[140:143], v[66:67], off offset:3072
	s_lshl_b32 s12, s1, 11
	s_lshl_b32 s13, s11, 11
	v_mov_b32_e32 v68, s12
	v_lshl_add_u64 v[144:145], v[20:21], 0, v[68:69]
	v_mov_b32_e32 v68, s13
	v_lshl_add_u64 v[146:147], v[20:21], 0, v[68:69]
	s_waitcnt vmcnt(8)
	v_mul_f32_e32 v60, v26, v26
	v_fmac_f32_e32 v60, v27, v27
	v_fmac_f32_e32 v60, v28, v28
	v_fmac_f32_e32 v60, v29, v29
	v_fmac_f32_e32 v60, v30, v30
	v_fmac_f32_e32 v60, v31, v31
	v_fmac_f32_e32 v60, v32, v32
	v_fmac_f32_e32 v60, v33, v33
	v_fmac_f32_e32 v60, v34, v34
	v_fmac_f32_e32 v60, v35, v35
	v_fmac_f32_e32 v60, v36, v36
	v_fmac_f32_e32 v60, v37, v37
	v_fmac_f32_e32 v60, v38, v38
	v_fmac_f32_e32 v60, v39, v39
	v_fmac_f32_e32 v60, v40, v40
	v_fmac_f32_e32 v60, v41, v41
	v_mul_f32_e32 v61, v42, v42
	v_fmac_f32_e32 v61, v43, v43
	v_fmac_f32_e32 v61, v44, v44
	v_fmac_f32_e32 v61, v45, v45
	v_fmac_f32_e32 v61, v46, v46
	v_fmac_f32_e32 v61, v47, v47
	v_fmac_f32_e32 v61, v48, v48
	v_fmac_f32_e32 v61, v49, v49
	v_fmac_f32_e32 v61, v50, v50
	v_fmac_f32_e32 v61, v51, v51
	v_fmac_f32_e32 v61, v52, v52
	v_fmac_f32_e32 v61, v53, v53
	v_fmac_f32_e32 v61, v54, v54
	v_fmac_f32_e32 v61, v55, v55
	v_fmac_f32_e32 v61, v56, v56
	v_fmac_f32_e32 v61, v57, v57
	v_lshlrev_b32_e32 v70, 2, v210
	v_xor_b32_e32 v70, 0x80, v70
	ds_swizzle_b32 v63, v61 offset:swizzle(SWAP,16)
	ds_swizzle_b32 v62, v60 offset:swizzle(SWAP,16)
	s_waitcnt lgkmcnt(0)
	v_pk_add_f32 v[60:61], v[60:61], v[62:63]
	ds_swizzle_b32 v63, v61 offset:swizzle(SWAP,8)
	ds_swizzle_b32 v62, v60 offset:swizzle(SWAP,8)
	s_waitcnt lgkmcnt(0)
	v_pk_add_f32 v[60:61], v[60:61], v[62:63]
	ds_swizzle_b32 v63, v61 offset:swizzle(SWAP,4)
	ds_swizzle_b32 v62, v60 offset:swizzle(SWAP,4)
	s_waitcnt lgkmcnt(0)
	v_pk_add_f32 v[60:61], v[60:61], v[62:63]
	ds_swizzle_b32 v63, v61 offset:swizzle(SWAP,2)
	ds_swizzle_b32 v62, v60 offset:swizzle(SWAP,2)
	s_waitcnt lgkmcnt(0)
	v_pk_add_f32 v[60:61], v[60:61], v[62:63]
	ds_swizzle_b32 v63, v61 offset:swizzle(SWAP,1)
	ds_swizzle_b32 v62, v60 offset:swizzle(SWAP,1)
	s_waitcnt lgkmcnt(0)
	v_pk_add_f32 v[60:61], v[60:61], v[62:63]
	ds_bpermute_b32 v63, v70, v61
	ds_bpermute_b32 v62, v70, v60
	s_waitcnt lgkmcnt(0)
	v_pk_add_f32 v[60:61], v[60:61], v[62:63]
	s_nop 0
	v_pk_fma_f32 v[60:61], v[60:61], s[58:59], v[154:155] op_sel_hi:[1,0,0]
	s_nop 0
	v_rsq_f32_e32 v60, v60
	v_rsq_f32_e32 v62, v61
	s_nop 0
	v_pk_mul_f32 v[26:27], v[26:27], v[60:61] op_sel_hi:[1,0]
	v_pk_mul_f32 v[26:27], v[2:3], v[26:27]
	v_pk_mul_f32 v[28:29], v[28:29], v[60:61] op_sel_hi:[1,0]
	v_pk_mul_f32 v[28:29], v[4:5], v[28:29]
	v_pk_mul_f32 v[30:31], v[30:31], v[60:61] op_sel_hi:[1,0]
	v_pk_mul_f32 v[30:31], v[6:7], v[30:31]
	v_pk_mul_f32 v[32:33], v[32:33], v[60:61] op_sel_hi:[1,0]
	v_pk_mul_f32 v[32:33], v[8:9], v[32:33]
	v_pk_mul_f32 v[34:35], v[34:35], v[60:61] op_sel_hi:[1,0]
	v_pk_mul_f32 v[34:35], v[10:11], v[34:35]
	v_pk_mul_f32 v[36:37], v[36:37], v[60:61] op_sel_hi:[1,0]
	v_pk_mul_f32 v[36:37], v[12:13], v[36:37]
	v_pk_mul_f32 v[38:39], v[38:39], v[60:61] op_sel_hi:[1,0]
	v_pk_mul_f32 v[38:39], v[14:15], v[38:39]
	v_pk_mul_f32 v[40:41], v[40:41], v[60:61] op_sel_hi:[1,0]
	v_pk_mul_f32 v[40:41], v[16:17], v[40:41]
	v_pk_mul_f32 v[42:43], v[42:43], v[62:63] op_sel_hi:[1,0]
	v_pk_mul_f32 v[42:43], v[2:3], v[42:43]
	v_pk_mul_f32 v[44:45], v[44:45], v[62:63] op_sel_hi:[1,0]
	v_pk_mul_f32 v[44:45], v[4:5], v[44:45]
	v_pk_mul_f32 v[46:47], v[46:47], v[62:63] op_sel_hi:[1,0]
	v_pk_mul_f32 v[46:47], v[6:7], v[46:47]
	v_pk_mul_f32 v[48:49], v[48:49], v[62:63] op_sel_hi:[1,0]
	v_pk_mul_f32 v[48:49], v[8:9], v[48:49]
	v_pk_mul_f32 v[50:51], v[50:51], v[62:63] op_sel_hi:[1,0]
	v_pk_mul_f32 v[50:51], v[10:11], v[50:51]
	v_pk_mul_f32 v[52:53], v[52:53], v[62:63] op_sel_hi:[1,0]
	v_pk_mul_f32 v[52:53], v[12:13], v[52:53]
	v_pk_mul_f32 v[54:55], v[54:55], v[62:63] op_sel_hi:[1,0]
	v_pk_mul_f32 v[54:55], v[14:15], v[54:55]
	v_pk_mul_f32 v[56:57], v[56:57], v[62:63] op_sel_hi:[1,0]
	v_pk_mul_f32 v[56:57], v[16:17], v[56:57]
	v_cvt_pk_bf16_f32 v26, v26, v27
	v_cvt_pk_bf16_f32 v27, v28, v29
	v_cvt_pk_bf16_f32 v30, v30, v31
	v_cvt_pk_bf16_f32 v31, v32, v33
	v_cvt_pk_bf16_f32 v34, v34, v35
	v_cvt_pk_bf16_f32 v35, v36, v37
	v_cvt_pk_bf16_f32 v38, v38, v39
	v_cvt_pk_bf16_f32 v39, v40, v41
	global_store_dwordx2 v[24:25], v[26:27], off sc1
	global_store_dwordx2 v[24:25], v[30:31], off offset:512 sc1
	global_store_dwordx2 v[24:25], v[34:35], off offset:1024 sc1
	global_store_dwordx2 v[24:25], v[38:39], off offset:1536 sc1
	v_cvt_pk_bf16_f32 v42, v42, v43
	v_cvt_pk_bf16_f32 v43, v44, v45
	v_cvt_pk_bf16_f32 v46, v46, v47
	v_cvt_pk_bf16_f32 v47, v48, v49
	v_cvt_pk_bf16_f32 v50, v50, v51
	v_cvt_pk_bf16_f32 v51, v52, v53
	v_cvt_pk_bf16_f32 v54, v54, v55
	v_cvt_pk_bf16_f32 v55, v56, v57
	global_store_dwordx2 v[58:59], v[42:43], off sc1
	global_store_dwordx2 v[58:59], v[46:47], off offset:512 sc1
	global_store_dwordx2 v[58:59], v[50:51], off offset:1024 sc1
	global_store_dwordx2 v[58:59], v[54:55], off offset:1536 sc1
; __device__ __forceinline__ void store8bf(bf16_t* p, f32x4 v0, f32x4 v1) { u32x4 w; w.x = cvt_pk_bf16(v0[0], v0[1]); w.y = cvt_pk_bf16(v0[2], v0[3]); w.z = cvt_pk_bf16(v1[0], v1[1]); w.w = cvt_pk_bf16(v1[2], v1[3]); *(u32x4*)p = w; }
; __device__ __forceinline__ void norm_phase(const float* H, const float* g, bf16_t* HN) {
;     ...
;   for (int row = gw; row < NREAL + 64; row += 2 * nw) {
;     const int row2 = row + nw < NREAL + 64 ? row + nw : row;
;     const float* p = H + (size_t)row * DM + lane * 8; const float* p2 = H + (size_t)row2 * DM + lane * 8; f32x4 v[4], u[4]; float ss = 0.f, ss2 = 0.f;
; #pragma unroll
;     for (int i = 0; i < 4; ++i) { v[i] = *(const f32x4*)(p + 512 * (i >> 1) + 4 * (i & 1)); u[i] = *(const f32x4*)(p2 + 512 * (i >> 1) + 4 * (i & 1)); }
; #pragma unroll
;     for (int i = 0; i < 4; ++i) { ss += v[i][0] * v[i][0] + v[i][1] * v[i][1] + v[i][2] * v[i][2] + v[i][3] * v[i][3]; ss2 += u[i][0] * u[i][0] + u[i][1] * u[i][1] + u[i][2] * u[i][2] + u[i][3] * u[i][3]; }
;     ss = wave_sum(ss); ss2 = wave_sum(ss2); const float rs = rsqrtf(ss * (1.0f / 1024.0f) + 1e-6f), rs2 = rsqrtf(ss2 * (1.0f / 1024.0f) + 1e-6f);
;     bf16_t* q = HN + (size_t)row * DM + lane * 8; bf16_t* q2 = HN + (size_t)row2 * DM + lane * 8;
; #pragma unroll
;     for (int i = 0; i < 2; ++i) { store8bf(q + 512 * i, v[2 * i] * rs * gv[2 * i], v[2 * i + 1] * rs * gv[2 * i + 1]); store8bf(q2 + 512 * i, u[2 * i] * rs2 * gv[2 * i], u[2 * i + 1] * rs2 * gv[2 * i + 1]); }
;   }
.Ln1_loop:
	s_add_i32 s0, s1, s9
	s_cmp_lt_i32 s0, s49
	s_cbranch_scc0 .Ln1_lastB
	s_add_i32 s11, s0, s8
	s_cmp_lt_i32 s11, s49
	s_cselect_b32 s11, s11, s0
	s_lshl_b32 s12, s0, 12
	s_lshl_b32 s13, s11, 12
	v_mov_b32_e32 v68, s12
	v_mov_b32_e32 v69, 0
	v_lshl_add_u64 v[64:65], v[18:19], 0, v[68:69]
	v_mov_b32_e32 v68, s13
	v_lshl_add_u64 v[66:67], v[18:19], 0, v[68:69]
	global_load_dwordx4 v[26:29], v[64:65], off
	global_load_dwordx4 v[30:33], v[64:65], off offset:1024
	global_load_dwordx4 v[34:37], v[64:65], off offset:2048
	global_load_dwordx4 v[38:41], v[64:65], off offset:3072
	global_load_dwordx4 v[42:45], v[66:67], off
	global_load_dwordx4 v[46:49], v[66:67], off offset:1024
	global_load_dwordx4 v[50:53], v[66:67], off offset:2048
	global_load_dwordx4 v[54:57], v[66:67], off offset:3072
	s_lshl_b32 s12, s0, 11
	s_lshl_b32 s13, s11, 11
	v_mov_b32_e32 v68, s12
	v_lshl_add_u64 v[24:25], v[20:21], 0, v[68:69]
	v_mov_b32_e32 v68, s13
	v_lshl_add_u64 v[58:59], v[20:21], 0, v[68:69]
	s_waitcnt vmcnt(16)
	v_mul_f32_e32 v60, v88, v88
	v_fmac_f32_e32 v60, v89, v89
	v_fmac_f32_e32 v60, v90, v90
	v_fmac_f32_e32 v60, v91, v91
	v_fmac_f32_e32 v60, v92, v92
	v_fmac_f32_e32 v60, v93, v93
	v_fmac_f32_e32 v60, v94, v94
	v_fmac_f32_e32 v60, v95, v95
	v_fmac_f32_e32 v60, v96, v96
	v_fmac_f32_e32 v60, v97, v97
	v_fmac_f32_e32 v60, v98, v98
	v_fmac_f32_e32 v60, v99, v99
	v_fmac_f32_e32 v60, v100, v100
	v_fmac_f32_e32 v60, v101, v101
	v_fmac_f32_e32 v60, v102, v102
	v_fmac_f32_e32 v60, v103, v103
	v_mul_f32_e32 v61, v128, v128
	v_fmac_f32_e32 v61, v129, v129
	v_fmac_f32_e32 v61, v130, v130
	v_fmac_f32_e32 v61, v131, v131
	v_fmac_f32_e32 v61, v132, v132
	v_fmac_f32_e32 v61, v133, v133
	v_fmac_f32_e32 v61, v134, v134
	v_fmac_f32_e32 v61, v135, v135
	v_fmac_f32_e32 v61, v136, v136
	v_fmac_f32_e32 v61, v137, v137
	v_fmac_f32_e32 v61, v138, v138
	v_fmac_f32_e32 v61, v139, v139
	v_fmac_f32_e32 v61, v140, v140
	v_fmac_f32_e32 v61, v141, v141
	v_fmac_f32_e32 v61, v142, v142
	v_fmac_f32_e32 v61, v143, v143
	v_lshlrev_b32_e32 v70, 2, v210
	v_xor_b32_e32 v70, 0x80, v70
	ds_swizzle_b32 v63, v61 offset:swizzle(SWAP,16)
	ds_swizzle_b32 v62, v60 offset:swizzle(SWAP,16)
	s_waitcnt lgkmcnt(0)
	v_pk_add_f32 v[60:61], v[60:61], v[62:63]
	ds_swizzle_b32 v63, v61 offset:swizzle(SWAP,8)
	ds_swizzle_b32 v62, v60 offset:swizzle(SWAP,8)
	s_waitcnt lgkmcnt(0)
	v_pk_add_f32 v[60:61], v[60:61], v[62:63]
	ds_swizzle_b32 v63, v61 offset:swizzle(SWAP,4)
	ds_swizzle_b32 v62, v60 offset:swizzle(SWAP,4)
	s_waitcnt lgkmcnt(0)
	v_pk_add_f32 v[60:61], v[60:61], v[62:63]
	ds_swizzle_b32 v63, v61 offset:swizzle(SWAP,2)
	ds_swizzle_b32 v62, v60 offset:swizzle(SWAP,2)
	s_waitcnt lgkmcnt(0)
	v_pk_add_f32 v[60:61], v[60:61], v[62:63]
	ds_swizzle_b32 v63, v61 offset:swizzle(SWAP,1)
	ds_swizzle_b32 v62, v60 offset:swizzle(SWAP,1)
	s_waitcnt lgkmcnt(0)
	v_pk_add_f32 v[60:61], v[60:61], v[62:63]
	ds_bpermute_b32 v63, v70, v61
	ds_bpermute_b32 v62, v70, v60
	s_waitcnt lgkmcnt(0)
	v_pk_add_f32 v[60:61], v[60:61], v[62:63]
	s_nop 0
	v_pk_fma_f32 v[60:61], v[60:61], s[58:59], v[154:155] op_sel_hi:[1,0,0]
	s_nop 0
	v_rsq_f32_e32 v60, v60
	v_rsq_f32_e32 v62, v61
	s_nop 0
	v_pk_mul_f32 v[88:89], v[88:89], v[60:61] op_sel_hi:[1,0]
	v_pk_mul_f32 v[88:89], v[2:3], v[88:89]
	v_pk_mul_f32 v[90:91], v[90:91], v[60:61] op_sel_hi:[1,0]
	v_pk_mul_f32 v[90:91], v[4:5], v[90:91]
	v_pk_mul_f32 v[92:93], v[92:93], v[60:61] op_sel_hi:[1,0]
	v_pk_mul_f32 v[92:93], v[6:7], v[92:93]
	v_pk_mul_f32 v[94:95], v[94:95], v[60:61] op_sel_hi:[1,0]
	v_pk_mul_f32 v[94:95], v[8:9], v[94:95]
	v_pk_mul_f32 v[96:97], v[96:97], v[60:61] op_sel_hi:[1,0]
	v_pk_mul_f32 v[96:97], v[10:11], v[96:97]
	v_pk_mul_f32 v[98:99], v[98:99], v[60:61] op_sel_hi:[1,0]
	v_pk_mul_f32 v[98:99], v[12:13], v[98:99]
	v_pk_mul_f32 v[100:101], v[100:101], v[60:61] op_sel_hi:[1,0]
	v_pk_mul_f32 v[100:101], v[14:15], v[100:101]
	v_pk_mul_f32 v[102:103], v[102:103], v[60:61] op_sel_hi:[1,0]
	v_pk_mul_f32 v[102:103], v[16:17], v[102:103]
	v_pk_mul_f32 v[128:129], v[128:129], v[62:63] op_sel_hi:[1,0]
	v_pk_mul_f32 v[128:129], v[2:3], v[128:129]
	v_pk_mul_f32 v[130:131], v[130:131], v[62:63] op_sel_hi:[1,0]
	v_pk_mul_f32 v[130:131], v[4:5], v[130:131]
	v_pk_mul_f32 v[132:133], v[132:133], v[62:63] op_sel_hi:[1,0]
	v_pk_mul_f32 v[132:133], v[6:7], v[132:133]
	v_pk_mul_f32 v[134:135], v[134:135], v[62:63] op_sel_hi:[1,0]
	v_pk_mul_f32 v[134:135], v[8:9], v[134:135]
	v_pk_mul_f32 v[136:137], v[136:137], v[62:63] op_sel_hi:[1,0]
	v_pk_mul_f32 v[136:137], v[10:11], v[136:137]
	v_pk_mul_f32 v[138:139], v[138:139], v[62:63] op_sel_hi:[1,0]
	v_pk_mul_f32 v[138:139], v[12:13], v[138:139]
	v_pk_mul_f32 v[140:141], v[140:141], v[62:63] op_sel_hi:[1,0]
	v_pk_mul_f32 v[140:141], v[14:15], v[140:141]
	v_pk_mul_f32 v[142:143], v[142:143], v[62:63] op_sel_hi:[1,0]
	v_pk_mul_f32 v[142:143], v[16:17], v[142:143]
	v_cvt_pk_bf16_f32 v88, v88, v89
	v_cvt_pk_bf16_f32 v89, v90, v91
	v_cvt_pk_bf16_f32 v92, v92, v93
	v_cvt_pk_bf16_f32 v93, v94, v95
	v_cvt_pk_bf16_f32 v96, v96, v97
	v_cvt_pk_bf16_f32 v97, v98, v99
	v_cvt_pk_bf16_f32 v100, v100, v101
	v_cvt_pk_bf16_f32 v101, v102, v103
	global_store_dwordx2 v[144:145], v[88:89], off sc1
	global_store_dwordx2 v[144:145], v[92:93], off offset:512 sc1
	global_store_dwordx2 v[144:145], v[96:97], off offset:1024 sc1
	global_store_dwordx2 v[144:145], v[100:101], off offset:1536 sc1
	v_cvt_pk_bf16_f32 v128, v128, v129
	v_cvt_pk_bf16_f32 v129, v130, v131
	v_cvt_pk_bf16_f32 v132, v132, v133
	v_cvt_pk_bf16_f32 v133, v134, v135
	v_cvt_pk_bf16_f32 v136, v136, v137
	v_cvt_pk_bf16_f32 v137, v138, v139
	v_cvt_pk_bf16_f32 v140, v140, v141
	v_cvt_pk_bf16_f32 v141, v142, v143
	global_store_dwordx2 v[146:147], v[128:129], off sc1
	global_store_dwordx2 v[146:147], v[132:133], off offset:512 sc1
	global_store_dwordx2 v[146:147], v[136:137], off offset:1024 sc1
	global_store_dwordx2 v[146:147], v[140:141], off offset:1536 sc1
	s_add_i32 s1, s0, s9
	s_cmp_lt_i32 s1, s49
	s_cbranch_scc0 .Ln1_lastA
; __device__ __forceinline__ void store8bf(bf16_t* p, f32x4 v0, f32x4 v1) { u32x4 w; w.x = cvt_pk_bf16(v0[0], v0[1]); w.y = cvt_pk_bf16(v0[2], v0[3]); w.z = cvt_pk_bf16(v1[0], v1[1]); w.w = cvt_pk_bf16(v1[2], v1[3]); *(u32x4*)p = w; }
; __device__ __forceinline__ void norm_phase(const float* H, const float* g, bf16_t* HN) {
;     ...
;   for (int row = gw; row < NREAL + 64; row += 2 * nw) {
;     const int row2 = row + nw < NREAL + 64 ? row + nw : row;
;     const float* p = H + (size_t)row * DM + lane * 8; const float* p2 = H + (size_t)row2 * DM + lane * 8; f32x4 v[4], u[4]; float ss = 0.f, ss2 = 0.f;
; #pragma unroll
;     for (int i = 0; i < 4; ++i) { v[i] = *(const f32x4*)(p + 512 * (i >> 1) + 4 * (i & 1)); u[i] = *(const f32x4*)(p2 + 512 * (i >> 1) + 4 * (i & 1)); }
; #pragma unroll
;     for (int i = 0; i < 4; ++i) { ss += v[i][0] * v[i][0] + v[i][1] * v[i][1] + v[i][2] * v[i][2] + v[i][3] * v[i][3]; ss2 += u[i][0] * u[i][0] + u[i][1] * u[i][1] + u[i][2] * u[i][2] + u[i][3] * u[i][3]; }
;     ss = wave_sum(ss); ss2 = wave_sum(ss2); const float rs = rsqrtf(ss * (1.0f / 1024.0f) + 1e-6f), rs2 = rsqrtf(ss2 * (1.0f / 1024.0f) + 1e-6f);
;     bf16_t* q = HN + (size_t)row * DM + lane * 8; bf16_t* q2 = HN + (size_t)row2 * DM + lane * 8;
; #pragma unroll
;     for (int i = 0; i < 2; ++i) { store8bf(q + 512 * i, v[2 * i] * rs * gv[2 * i], v[2 * i + 1] * rs * gv[2 * i + 1]); store8bf(q2 + 512 * i, u[2 * i] * rs2 * gv[2 * i], u[2 * i + 1] * rs2 * gv[2 * i + 1]); }
;   }
	s_add_i32 s11, s1, s8
	s_cmp_lt_i32 s11, s49
	s_cselect_b32 s11, s11, s1
	s_lshl_b32 s12, s1, 12
	s_lshl_b32 s13, s11, 12
	v_mov_b32_e32 v68, s12
	v_mov_b32_e32 v69, 0
	v_lshl_add_u64 v[64:65], v[18:19], 0, v[68:69]
	v_mov_b32_e32 v68, s13
	v_lshl_add_u64 v[66:67], v[18:19], 0, v[68:69]
	global_load_dwordx4 v[88:91], v[64:65], off
	global_load_dwordx4 v[92:95], v[64:65], off offset:1024
	global_load_dwordx4 v[96:99], v[64:65], off offset:2048
	global_load_dwordx4 v[100:103], v[64:65], off offset:3072
	global_load_dwordx4 v[128:131], v[66:67], off
	global_load_dwordx4 v[132:135], v[66:67], off offset:1024
	global_load_dwordx4 v[136:139], v[66:67], off offset:2048
	global_load_dwordx4 v[140:143], v[66:67], off offset:3072
	s_lshl_b32 s12, s1, 11
	s_lshl_b32 s13, s11, 11
	v_mov_b32_e32 v68, s12
	v_lshl_add_u64 v[144:145], v[20:21], 0, v[68:69]
	v_mov_b32_e32 v68, s13
	v_lshl_add_u64 v[146:147], v[20:21], 0, v[68:69]
	s_waitcnt vmcnt(16)
	v_mul_f32_e32 v60, v26, v26
	v_fmac_f32_e32 v60, v27, v27
	v_fmac_f32_e32 v60, v28, v28
	v_fmac_f32_e32 v60, v29, v29
	v_fmac_f32_e32 v60, v30, v30
	v_fmac_f32_e32 v60, v31, v31
	v_fmac_f32_e32 v60, v32, v32
	v_fmac_f32_e32 v60, v33, v33
	v_fmac_f32_e32 v60, v34, v34
	v_fmac_f32_e32 v60, v35, v35
	v_fmac_f32_e32 v60, v36, v36
	v_fmac_f32_e32 v60, v37, v37
	v_fmac_f32_e32 v60, v38, v38
	v_fmac_f32_e32 v60, v39, v39
	v_fmac_f32_e32 v60, v40, v40
	v_fmac_f32_e32 v60, v41, v41
	v_mul_f32_e32 v61, v42, v42
	v_fmac_f32_e32 v61, v43, v43
	v_fmac_f32_e32 v61, v44, v44
	v_fmac_f32_e32 v61, v45, v45
	v_fmac_f32_e32 v61, v46, v46
	v_fmac_f32_e32 v61, v47, v47
	v_fmac_f32_e32 v61, v48, v48
	v_fmac_f32_e32 v61, v49, v49
	v_fmac_f32_e32 v61, v50, v50
	v_fmac_f32_e32 v61, v51, v51
	v_fmac_f32_e32 v61, v52, v52
	v_fmac_f32_e32 v61, v53, v53
	v_fmac_f32_e32 v61, v54, v54
	v_fmac_f32_e32 v61, v55, v55
	v_fmac_f32_e32 v61, v56, v56
	v_fmac_f32_e32 v61, v57, v57
	v_lshlrev_b32_e32 v70, 2, v210
	v_xor_b32_e32 v70, 0x80, v70
	ds_swizzle_b32 v63, v61 offset:swizzle(SWAP,16)
	ds_swizzle_b32 v62, v60 offset:swizzle(SWAP,16)
	s_waitcnt lgkmcnt(0)
	v_pk_add_f32 v[60:61], v[60:61], v[62:63]
	ds_swizzle_b32 v63, v61 offset:swizzle(SWAP,8)
	ds_swizzle_b32 v62, v60 offset:swizzle(SWAP,8)
	s_waitcnt lgkmcnt(0)
	v_pk_add_f32 v[60:61], v[60:61], v[62:63]
	ds_swizzle_b32 v63, v61 offset:swizzle(SWAP,4)
	ds_swizzle_b32 v62, v60 offset:swizzle(SWAP,4)
	s_waitcnt lgkmcnt(0)
	v_pk_add_f32 v[60:61], v[60:61], v[62:63]
	ds_swizzle_b32 v63, v61 offset:swizzle(SWAP,2)
	ds_swizzle_b32 v62, v60 offset:swizzle(SWAP,2)
	s_waitcnt lgkmcnt(0)
	v_pk_add_f32 v[60:61], v[60:61], v[62:63]
	ds_swizzle_b32 v63, v61 offset:swizzle(SWAP,1)
	ds_swizzle_b32 v62, v60 offset:swizzle(SWAP,1)
	s_waitcnt lgkmcnt(0)
	v_pk_add_f32 v[60:61], v[60:61], v[62:63]
	ds_bpermute_b32 v63, v70, v61
	ds_bpermute_b32 v62, v70, v60
	s_waitcnt lgkmcnt(0)
	v_pk_add_f32 v[60:61], v[60:61], v[62:63]
	s_nop 0
	v_pk_fma_f32 v[60:61], v[60:61], s[58:59], v[154:155] op_sel_hi:[1,0,0]
	s_nop 0
	v_rsq_f32_e32 v60, v60
	v_rsq_f32_e32 v62, v61
	s_nop 0
	v_pk_mul_f32 v[26:27], v[26:27], v[60:61] op_sel_hi:[1,0]
	v_pk_mul_f32 v[26:27], v[2:3], v[26:27]
	v_pk_mul_f32 v[28:29], v[28:29], v[60:61] op_sel_hi:[1,0]
	v_pk_mul_f32 v[28:29], v[4:5], v[28:29]
	v_pk_mul_f32 v[30:31], v[30:31], v[60:61] op_sel_hi:[1,0]
	v_pk_mul_f32 v[30:31], v[6:7], v[30:31]
	v_pk_mul_f32 v[32:33], v[32:33], v[60:61] op_sel_hi:[1,0]
	v_pk_mul_f32 v[32:33], v[8:9], v[32:33]
	v_pk_mul_f32 v[34:35], v[34:35], v[60:61] op_sel_hi:[1,0]
	v_pk_mul_f32 v[34:35], v[10:11], v[34:35]
	v_pk_mul_f32 v[36:37], v[36:37], v[60:61] op_sel_hi:[1,0]
	v_pk_mul_f32 v[36:37], v[12:13], v[36:37]
	v_pk_mul_f32 v[38:39], v[38:39], v[60:61] op_sel_hi:[1,0]
	v_pk_mul_f32 v[38:39], v[14:15], v[38:39]
	v_pk_mul_f32 v[40:41], v[40:41], v[60:61] op_sel_hi:[1,0]
	v_pk_mul_f32 v[40:41], v[16:17], v[40:41]
	v_pk_mul_f32 v[42:43], v[42:43], v[62:63] op_sel_hi:[1,0]
	v_pk_mul_f32 v[42:43], v[2:3], v[42:43]
	v_pk_mul_f32 v[44:45], v[44:45], v[62:63] op_sel_hi:[1,0]
	v_pk_mul_f32 v[44:45], v[4:5], v[44:45]
	v_pk_mul_f32 v[46:47], v[46:47], v[62:63] op_sel_hi:[1,0]
	v_pk_mul_f32 v[46:47], v[6:7], v[46:47]
	v_pk_mul_f32 v[48:49], v[48:49], v[62:63] op_sel_hi:[1,0]
	v_pk_mul_f32 v[48:49], v[8:9], v[48:49]
	v_pk_mul_f32 v[50:51], v[50:51], v[62:63] op_sel_hi:[1,0]
	v_pk_mul_f32 v[50:51], v[10:11], v[50:51]
	v_pk_mul_f32 v[52:53], v[52:53], v[62:63] op_sel_hi:[1,0]
	v_pk_mul_f32 v[52:53], v[12:13], v[52:53]
	v_pk_mul_f32 v[54:55], v[54:55], v[62:63] op_sel_hi:[1,0]
	v_pk_mul_f32 v[54:55], v[14:15], v[54:55]
	v_pk_mul_f32 v[56:57], v[56:57], v[62:63] op_sel_hi:[1,0]
	v_pk_mul_f32 v[56:57], v[16:17], v[56:57]
	v_cvt_pk_bf16_f32 v26, v26, v27
	v_cvt_pk_bf16_f32 v27, v28, v29
	v_cvt_pk_bf16_f32 v30, v30, v31
	v_cvt_pk_bf16_f32 v31, v32, v33
	v_cvt_pk_bf16_f32 v34, v34, v35
	v_cvt_pk_bf16_f32 v35, v36, v37
	v_cvt_pk_bf16_f32 v38, v38, v39
	v_cvt_pk_bf16_f32 v39, v40, v41
	global_store_dwordx2 v[24:25], v[26:27], off sc1
	global_store_dwordx2 v[24:25], v[30:31], off offset:512 sc1
	global_store_dwordx2 v[24:25], v[34:35], off offset:1024 sc1
	global_store_dwordx2 v[24:25], v[38:39], off offset:1536 sc1
	v_cvt_pk_bf16_f32 v42, v42, v43
	v_cvt_pk_bf16_f32 v43, v44, v45
	v_cvt_pk_bf16_f32 v46, v46, v47
	v_cvt_pk_bf16_f32 v47, v48, v49
	v_cvt_pk_bf16_f32 v50, v50, v51
	v_cvt_pk_bf16_f32 v51, v52, v53
	v_cvt_pk_bf16_f32 v54, v54, v55
	v_cvt_pk_bf16_f32 v55, v56, v57
	global_store_dwordx2 v[58:59], v[42:43], off sc1
	global_store_dwordx2 v[58:59], v[46:47], off offset:512 sc1
	global_store_dwordx2 v[58:59], v[50:51], off offset:1024 sc1
	global_store_dwordx2 v[58:59], v[54:55], off offset:1536 sc1
	s_branch .Ln1_loop
; __device__ __forceinline__ void store8bf(bf16_t* p, f32x4 v0, f32x4 v1) { u32x4 w; w.x = cvt_pk_bf16(v0[0], v0[1]); w.y = cvt_pk_bf16(v0[2], v0[3]); w.z = cvt_pk_bf16(v1[0], v1[1]); w.w = cvt_pk_bf16(v1[2], v1[3]); *(u32x4*)p = w; }
; __device__ __forceinline__ void norm_phase(const float* H, const float* g, bf16_t* HN) {
;     ...
;     const float* p = H + (size_t)row * DM + lane * 8; const float* p2 = H + (size_t)row2 * DM + lane * 8; f32x4 v[4], u[4]; float ss = 0.f, ss2 = 0.f;
; #pragma unroll
;     for (int i = 0; i < 4; ++i) { v[i] = *(const f32x4*)(p + 512 * (i >> 1) + 4 * (i & 1)); u[i] = *(const f32x4*)(p2 + 512 * (i >> 1) + 4 * (i & 1)); }
; #pragma unroll
;     for (int i = 0; i < 4; ++i) { ss += v[i][0] * v[i][0] + v[i][1] * v[i][1] + v[i][2] * v[i][2] + v[i][3] * v[i][3]; ss2 += u[i][0] * u[i][0] + u[i][1] * u[i][1] + u[i][2] * u[i][2] + u[i][3] * u[i][3]; }
;     ss = wave_sum(ss); ss2 = wave_sum(ss2); const float rs = rsqrtf(ss * (1.0f / 1024.0f) + 1e-6f), rs2 = rsqrtf(ss2 * (1.0f / 1024.0f) + 1e-6f);
;     bf16_t* q = HN + (size_t)row * DM + lane * 8; bf16_t* q2 = HN + (size_t)row2 * DM + lane * 8;
; #pragma unroll
;     for (int i = 0; i < 2; ++i) { store8bf(q + 512 * i, v[2 * i] * rs * gv[2 * i], v[2 * i + 1] * rs * gv[2 * i + 1]); store8bf(q2 + 512 * i, u[2 * i] * rs2 * gv[2 * i], u[2 * i + 1] * rs2 * gv[2 * i + 1]); }
.Ln1_lastA_first:
	s_waitcnt vmcnt(0)
	v_mul_f32_e32 v60, v26, v26
	v_fmac_f32_e32 v60, v27, v27
	v_fmac_f32_e32 v60, v28, v28
	v_fmac_f32_e32 v60, v29, v29
	v_fmac_f32_e32 v60, v30, v30
	v_fmac_f32_e32 v60, v31, v31
	v_fmac_f32_e32 v60, v32, v32
	v_fmac_f32_e32 v60, v33, v33
	v_fmac_f32_e32 v60, v34, v34
	v_fmac_f32_e32 v60, v35, v35
	v_fmac_f32_e32 v60, v36, v36
	v_fmac_f32_e32 v60, v37, v37
	v_fmac_f32_e32 v60, v38, v38
	v_fmac_f32_e32 v60, v39, v39
	v_fmac_f32_e32 v60, v40, v40
	v_fmac_f32_e32 v60, v41, v41
	v_mul_f32_e32 v61, v42, v42
	v_fmac_f32_e32 v61, v43, v43
	v_fmac_f32_e32 v61, v44, v44
	v_fmac_f32_e32 v61, v45, v45
	v_fmac_f32_e32 v61, v46, v46
	v_fmac_f32_e32 v61, v47, v47
	v_fmac_f32_e32 v61, v48, v48
	v_fmac_f32_e32 v61, v49, v49
	v_fmac_f32_e32 v61, v50, v50
	v_fmac_f32_e32 v61, v51, v51
	v_fmac_f32_e32 v61, v52, v52
	v_fmac_f32_e32 v61, v53, v53
	v_fmac_f32_e32 v61, v54, v54
	v_fmac_f32_e32 v61, v55, v55
	v_fmac_f32_e32 v61, v56, v56
	v_fmac_f32_e32 v61, v57, v57
	v_lshlrev_b32_e32 v70, 2, v210
	v_xor_b32_e32 v70, 0x80, v70
	ds_swizzle_b32 v63, v61 offset:swizzle(SWAP,16)
	ds_swizzle_b32 v62, v60 offset:swizzle(SWAP,16)
	s_waitcnt lgkmcnt(0)
	v_pk_add_f32 v[60:61], v[60:61], v[62:63]
	ds_swizzle_b32 v63, v61 offset:swizzle(SWAP,8)
	ds_swizzle_b32 v62, v60 offset:swizzle(SWAP,8)
	s_waitcnt lgkmcnt(0)
	v_pk_add_f32 v[60:61], v[60:61], v[62:63]
	ds_swizzle_b32 v63, v61 offset:swizzle(SWAP,4)
	ds_swizzle_b32 v62, v60 offset:swizzle(SWAP,4)
	s_waitcnt lgkmcnt(0)
	v_pk_add_f32 v[60:61], v[60:61], v[62:63]
	ds_swizzle_b32 v63, v61 offset:swizzle(SWAP,2)
	ds_swizzle_b32 v62, v60 offset:swizzle(SWAP,2)
	s_waitcnt lgkmcnt(0)
	v_pk_add_f32 v[60:61], v[60:61], v[62:63]
	ds_swizzle_b32 v63, v61 offset:swizzle(SWAP,1)
	ds_swizzle_b32 v62, v60 offset:swizzle(SWAP,1)
	s_waitcnt lgkmcnt(0)
	v_pk_add_f32 v[60:61], v[60:61], v[62:63]
	ds_bpermute_b32 v63, v70, v61
	ds_bpermute_b32 v62, v70, v60
	s_waitcnt lgkmcnt(0)
	v_pk_add_f32 v[60:61], v[60:61], v[62:63]
	s_nop 0
	v_pk_fma_f32 v[60:61], v[60:61], s[58:59], v[154:155] op_sel_hi:[1,0,0]
	s_nop 0
	v_rsq_f32_e32 v60, v60
	v_rsq_f32_e32 v62, v61
	s_nop 0
	v_pk_mul_f32 v[26:27], v[26:27], v[60:61] op_sel_hi:[1,0]
	v_pk_mul_f32 v[26:27], v[2:3], v[26:27]
	v_pk_mul_f32 v[28:29], v[28:29], v[60:61] op_sel_hi:[1,0]
	v_pk_mul_f32 v[28:29], v[4:5], v[28:29]
	v_pk_mul_f32 v[30:31], v[30:31], v[60:61] op_sel_hi:[1,0]
	v_pk_mul_f32 v[30:31], v[6:7], v[30:31]
	v_pk_mul_f32 v[32:33], v[32:33], v[60:61] op_sel_hi:[1,0]
	v_pk_mul_f32 v[32:33], v[8:9], v[32:33]
	v_pk_mul_f32 v[34:35], v[34:35], v[60:61] op_sel_hi:[1,0]
	v_pk_mul_f32 v[34:35], v[10:11], v[34:35]
	v_pk_mul_f32 v[36:37], v[36:37], v[60:61] op_sel_hi:[1,0]
	v_pk_mul_f32 v[36:37], v[12:13], v[36:37]
	v_pk_mul_f32 v[38:39], v[38:39], v[60:61] op_sel_hi:[1,0]
	v_pk_mul_f32 v[38:39], v[14:15], v[38:39]
	v_pk_mul_f32 v[40:41], v[40:41], v[60:61] op_sel_hi:[1,0]
	v_pk_mul_f32 v[40:41], v[16:17], v[40:41]
	v_pk_mul_f32 v[42:43], v[42:43], v[62:63] op_sel_hi:[1,0]
	v_pk_mul_f32 v[42:43], v[2:3], v[42:43]
	v_pk_mul_f32 v[44:45], v[44:45], v[62:63] op_sel_hi:[1,0]
	v_pk_mul_f32 v[44:45], v[4:5], v[44:45]
	v_pk_mul_f32 v[46:47], v[46:47], v[62:63] op_sel_hi:[1,0]
	v_pk_mul_f32 v[46:47], v[6:7], v[46:47]
	v_pk_mul_f32 v[48:49], v[48:49], v[62:63] op_sel_hi:[1,0]
	v_pk_mul_f32 v[48:49], v[8:9], v[48:49]
	v_pk_mul_f32 v[50:51], v[50:51], v[62:63] op_sel_hi:[1,0]
	v_pk_mul_f32 v[50:51], v[10:11], v[50:51]
	v_pk_mul_f32 v[52:53], v[52:53], v[62:63] op_sel_hi:[1,0]
	v_pk_mul_f32 v[52:53], v[12:13], v[52:53]
	v_pk_mul_f32 v[54:55], v[54:55], v[62:63] op_sel_hi:[1,0]
	v_pk_mul_f32 v[54:55], v[14:15], v[54:55]
	v_pk_mul_f32 v[56:57], v[56:57], v[62:63] op_sel_hi:[1,0]
	v_pk_mul_f32 v[56:57], v[16:17], v[56:57]
	v_cvt_pk_bf16_f32 v26, v26, v27
	v_cvt_pk_bf16_f32 v27, v28, v29
	v_cvt_pk_bf16_f32 v30, v30, v31
	v_cvt_pk_bf16_f32 v31, v32, v33
	v_cvt_pk_bf16_f32 v34, v34, v35
	v_cvt_pk_bf16_f32 v35, v36, v37
	v_cvt_pk_bf16_f32 v38, v38, v39
	v_cvt_pk_bf16_f32 v39, v40, v41
	global_store_dwordx2 v[24:25], v[26:27], off sc1
	global_store_dwordx2 v[24:25], v[30:31], off offset:512 sc1
	global_store_dwordx2 v[24:25], v[34:35], off offset:1024 sc1
	global_store_dwordx2 v[24:25], v[38:39], off offset:1536 sc1
	v_cvt_pk_bf16_f32 v42, v42, v43
	v_cvt_pk_bf16_f32 v43, v44, v45
	v_cvt_pk_bf16_f32 v46, v46, v47
	v_cvt_pk_bf16_f32 v47, v48, v49
	v_cvt_pk_bf16_f32 v50, v50, v51
	v_cvt_pk_bf16_f32 v51, v52, v53
	v_cvt_pk_bf16_f32 v54, v54, v55
	v_cvt_pk_bf16_f32 v55, v56, v57
	global_store_dwordx2 v[58:59], v[42:43], off sc1
	global_store_dwordx2 v[58:59], v[46:47], off offset:512 sc1
	global_store_dwordx2 v[58:59], v[50:51], off offset:1024 sc1
	global_store_dwordx2 v[58:59], v[54:55], off offset:1536 sc1
	s_branch .Ln1_done
; __device__ __forceinline__ void store8bf(bf16_t* p, f32x4 v0, f32x4 v1) { u32x4 w; w.x = cvt_pk_bf16(v0[0], v0[1]); w.y = cvt_pk_bf16(v0[2], v0[3]); w.z = cvt_pk_bf16(v1[0], v1[1]); w.w = cvt_pk_bf16(v1[2], v1[3]); *(u32x4*)p = w; }
; __device__ __forceinline__ void norm_phase(const float* H, const float* g, bf16_t* HN) {
;     ...
;     const float* p = H + (size_t)row * DM + lane * 8; const float* p2 = H + (size_t)row2 * DM + lane * 8; f32x4 v[4], u[4]; float ss = 0.f, ss2 = 0.f;
; #pragma unroll
;     for (int i = 0; i < 4; ++i) { v[i] = *(const f32x4*)(p + 512 * (i >> 1) + 4 * (i & 1)); u[i] = *(const f32x4*)(p2 + 512 * (i >> 1) + 4 * (i & 1)); }
; #pragma unroll
;     for (int i = 0; i < 4; ++i) { ss += v[i][0] * v[i][0] + v[i][1] * v[i][1] + v[i][2] * v[i][2] + v[i][3] * v[i][3]; ss2 += u[i][0] * u[i][0] + u[i][1] * u[i][1] + u[i][2] * u[i][2] + u[i][3] * u[i][3]; }
;     ss = wave_sum(ss); ss2 = wave_sum(ss2); const float rs = rsqrtf(ss * (1.0f / 1024.0f) + 1e-6f), rs2 = rsqrtf(ss2 * (1.0f / 1024.0f) + 1e-6f);
;     bf16_t* q = HN + (size_t)row * DM + lane * 8; bf16_t* q2 = HN + (size_t)row2 * DM + lane * 8;
; #pragma unroll
;     for (int i = 0; i < 2; ++i) { store8bf(q + 512 * i, v[2 * i] * rs * gv[2 * i], v[2 * i + 1] * rs * gv[2 * i + 1]); store8bf(q2 + 512 * i, u[2 * i] * rs2 * gv[2 * i], u[2 * i + 1] * rs2 * gv[2 * i + 1]); }
.Ln1_lastB:
	s_waitcnt vmcnt(0)
	v_mul_f32_e32 v60, v88, v88
	v_fmac_f32_e32 v60, v89, v89
	v_fmac_f32_e32 v60, v90, v90
	v_fmac_f32_e32 v60, v91, v91
	v_fmac_f32_e32 v60, v92, v92
	v_fmac_f32_e32 v60, v93, v93
	v_fmac_f32_e32 v60, v94, v94
	v_fmac_f32_e32 v60, v95, v95
	v_fmac_f32_e32 v60, v96, v96
	v_fmac_f32_e32 v60, v97, v97
	v_fmac_f32_e32 v60, v98, v98
	v_fmac_f32_e32 v60, v99, v99
	v_fmac_f32_e32 v60, v100, v100
	v_fmac_f32_e32 v60, v101, v101
	v_fmac_f32_e32 v60, v102, v102
	v_fmac_f32_e32 v60, v103, v103
	v_mul_f32_e32 v61, v128, v128
	v_fmac_f32_e32 v61, v129, v129
	v_fmac_f32_e32 v61, v130, v130
	v_fmac_f32_e32 v61, v131, v131
	v_fmac_f32_e32 v61, v132, v132
	v_fmac_f32_e32 v61, v133, v133
	v_fmac_f32_e32 v61, v134, v134
	v_fmac_f32_e32 v61, v135, v135
	v_fmac_f32_e32 v61, v136, v136
	v_fmac_f32_e32 v61, v137, v137
	v_fmac_f32_e32 v61, v138, v138
	v_fmac_f32_e32 v61, v139, v139
	v_fmac_f32_e32 v61, v140, v140
	v_fmac_f32_e32 v61, v141, v141
	v_fmac_f32_e32 v61, v142, v142
	v_fmac_f32_e32 v61, v143, v143
	v_lshlrev_b32_e32 v70, 2, v210
	v_xor_b32_e32 v70, 0x80, v70
	ds_swizzle_b32 v63, v61 offset:swizzle(SWAP,16)
	ds_swizzle_b32 v62, v60 offset:swizzle(SWAP,16)
	s_waitcnt lgkmcnt(0)
	v_pk_add_f32 v[60:61], v[60:61], v[62:63]
	ds_swizzle_b32 v63, v61 offset:swizzle(SWAP,8)
	ds_swizzle_b32 v62, v60 offset:swizzle(SWAP,8)
	s_waitcnt lgkmcnt(0)
	v_pk_add_f32 v[60:61], v[60:61], v[62:63]
	ds_swizzle_b32 v63, v61 offset:swizzle(SWAP,4)
	ds_swizzle_b32 v62, v60 offset:swizzle(SWAP,4)
	s_waitcnt lgkmcnt(0)
	v_pk_add_f32 v[60:61], v[60:61], v[62:63]
	ds_swizzle_b32 v63, v61 offset:swizzle(SWAP,2)
	ds_swizzle_b32 v62, v60 offset:swizzle(SWAP,2)
	s_waitcnt lgkmcnt(0)
	v_pk_add_f32 v[60:61], v[60:61], v[62:63]
	ds_swizzle_b32 v63, v61 offset:swizzle(SWAP,1)
	ds_swizzle_b32 v62, v60 offset:swizzle(SWAP,1)
	s_waitcnt lgkmcnt(0)
	v_pk_add_f32 v[60:61], v[60:61], v[62:63]
	ds_bpermute_b32 v63, v70, v61
	ds_bpermute_b32 v62, v70, v60
	s_waitcnt lgkmcnt(0)
	v_pk_add_f32 v[60:61], v[60:61], v[62:63]
	s_nop 0
	v_pk_fma_f32 v[60:61], v[60:61], s[58:59], v[154:155] op_sel_hi:[1,0,0]
	s_nop 0
	v_rsq_f32_e32 v60, v60
	v_rsq_f32_e32 v62, v61
	s_nop 0
	v_pk_mul_f32 v[88:89], v[88:89], v[60:61] op_sel_hi:[1,0]
	v_pk_mul_f32 v[88:89], v[2:3], v[88:89]
	v_pk_mul_f32 v[90:91], v[90:91], v[60:61] op_sel_hi:[1,0]
	v_pk_mul_f32 v[90:91], v[4:5], v[90:91]
	v_pk_mul_f32 v[92:93], v[92:93], v[60:61] op_sel_hi:[1,0]
	v_pk_mul_f32 v[92:93], v[6:7], v[92:93]
	v_pk_mul_f32 v[94:95], v[94:95], v[60:61] op_sel_hi:[1,0]
	v_pk_mul_f32 v[94:95], v[8:9], v[94:95]
	v_pk_mul_f32 v[96:97], v[96:97], v[60:61] op_sel_hi:[1,0]
	v_pk_mul_f32 v[96:97], v[10:11], v[96:97]
	v_pk_mul_f32 v[98:99], v[98:99], v[60:61] op_sel_hi:[1,0]
	v_pk_mul_f32 v[98:99], v[12:13], v[98:99]
	v_pk_mul_f32 v[100:101], v[100:101], v[60:61] op_sel_hi:[1,0]
	v_pk_mul_f32 v[100:101], v[14:15], v[100:101]
	v_pk_mul_f32 v[102:103], v[102:103], v[60:61] op_sel_hi:[1,0]
	v_pk_mul_f32 v[102:103], v[16:17], v[102:103]
	v_pk_mul_f32 v[128:129], v[128:129], v[62:63] op_sel_hi:[1,0]
	v_pk_mul_f32 v[128:129], v[2:3], v[128:129]
	v_pk_mul_f32 v[130:131], v[130:131], v[62:63] op_sel_hi:[1,0]
	v_pk_mul_f32 v[130:131], v[4:5], v[130:131]
	v_pk_mul_f32 v[132:133], v[132:133], v[62:63] op_sel_hi:[1,0]
	v_pk_mul_f32 v[132:133], v[6:7], v[132:133]
	v_pk_mul_f32 v[134:135], v[134:135], v[62:63] op_sel_hi:[1,0]
	v_pk_mul_f32 v[134:135], v[8:9], v[134:135]
	v_pk_mul_f32 v[136:137], v[136:137], v[62:63] op_sel_hi:[1,0]
	v_pk_mul_f32 v[136:137], v[10:11], v[136:137]
	v_pk_mul_f32 v[138:139], v[138:139], v[62:63] op_sel_hi:[1,0]
	v_pk_mul_f32 v[138:139], v[12:13], v[138:139]
	v_pk_mul_f32 v[140:141], v[140:141], v[62:63] op_sel_hi:[1,0]
	v_pk_mul_f32 v[140:141], v[14:15], v[140:141]
	v_pk_mul_f32 v[142:143], v[142:143], v[62:63] op_sel_hi:[1,0]
	v_pk_mul_f32 v[142:143], v[16:17], v[142:143]
	v_cvt_pk_bf16_f32 v88, v88, v89
	v_cvt_pk_bf16_f32 v89, v90, v91
	v_cvt_pk_bf16_f32 v92, v92, v93
	v_cvt_pk_bf16_f32 v93, v94, v95
	v_cvt_pk_bf16_f32 v96, v96, v97
	v_cvt_pk_bf16_f32 v97, v98, v99
	v_cvt_pk_bf16_f32 v100, v100, v101
	v_cvt_pk_bf16_f32 v101, v102, v103
	global_store_dwordx2 v[144:145], v[88:89], off sc1
	global_store_dwordx2 v[144:145], v[92:93], off offset:512 sc1
	global_store_dwordx2 v[144:145], v[96:97], off offset:1024 sc1
	global_store_dwordx2 v[144:145], v[100:101], off offset:1536 sc1
	v_cvt_pk_bf16_f32 v128, v128, v129
	v_cvt_pk_bf16_f32 v129, v130, v131
	v_cvt_pk_bf16_f32 v132, v132, v133
	v_cvt_pk_bf16_f32 v133, v134, v135
	v_cvt_pk_bf16_f32 v136, v136, v137
	v_cvt_pk_bf16_f32 v137, v138, v139
	v_cvt_pk_bf16_f32 v140, v140, v141
	v_cvt_pk_bf16_f32 v141, v142, v143
	global_store_dwordx2 v[146:147], v[128:129], off sc1
	global_store_dwordx2 v[146:147], v[132:133], off offset:512 sc1
	global_store_dwordx2 v[146:147], v[136:137], off offset:1024 sc1
	global_store_dwordx2 v[146:147], v[140:141], off offset:1536 sc1
	s_branch .Ln1_done
; __device__ __forceinline__ void store8bf(bf16_t* p, f32x4 v0, f32x4 v1) { u32x4 w; w.x = cvt_pk_bf16(v0[0], v0[1]); w.y = cvt_pk_bf16(v0[2], v0[3]); w.z = cvt_pk_bf16(v1[0], v1[1]); w.w = cvt_pk_bf16(v1[2], v1[3]); *(u32x4*)p = w; }
; __device__ __forceinline__ void norm_phase(const float* H, const float* g, bf16_t* HN) {
;     ...
;     const float* p = H + (size_t)row * DM + lane * 8; const float* p2 = H + (size_t)row2 * DM + lane * 8; f32x4 v[4], u[4]; float ss = 0.f, ss2 = 0.f;
; #pragma unroll
;     for (int i = 0; i < 4; ++i) { v[i] = *(const f32x4*)(p + 512 * (i >> 1) + 4 * (i & 1)); u[i] = *(const f32x4*)(p2 + 512 * (i >> 1) + 4 * (i & 1)); }
; #pragma unroll
;     for (int i = 0; i < 4; ++i) { ss += v[i][0] * v[i][0] + v[i][1] * v[i][1] + v[i][2] * v[i][2] + v[i][3] * v[i][3]; ss2 += u[i][0] * u[i][0] + u[i][1] * u[i][1] + u[i][2] * u[i][2] + u[i][3] * u[i][3]; }
;     ss = wave_sum(ss); ss2 = wave_sum(ss2); const float rs = rsqrtf(ss * (1.0f / 1024.0f) + 1e-6f), rs2 = rsqrtf(ss2 * (1.0f / 1024.0f) + 1e-6f);
;     bf16_t* q = HN + (size_t)row * DM + lane * 8; bf16_t* q2 = HN + (size_t)row2 * DM + lane * 8;
; #pragma unroll
;     for (int i = 0; i < 2; ++i) { store8bf(q + 512 * i, v[2 * i] * rs * gv[2 * i], v[2 * i + 1] * rs * gv[2 * i + 1]); store8bf(q2 + 512 * i, u[2 * i] * rs2 * gv[2 * i], u[2 * i + 1] * rs2 * gv[2 * i + 1]); }
.Ln1_lastA:
	s_waitcnt vmcnt(0)
	v_mul_f32_e32 v60, v26, v26
	v_fmac_f32_e32 v60, v27, v27
	v_fmac_f32_e32 v60, v28, v28
	v_fmac_f32_e32 v60, v29, v29
	v_fmac_f32_e32 v60, v30, v30
	v_fmac_f32_e32 v60, v31, v31
	v_fmac_f32_e32 v60, v32, v32
	v_fmac_f32_e32 v60, v33, v33
	v_fmac_f32_e32 v60, v34, v34
	v_fmac_f32_e32 v60, v35, v35
	v_fmac_f32_e32 v60, v36, v36
	v_fmac_f32_e32 v60, v37, v37
	v_fmac_f32_e32 v60, v38, v38
	v_fmac_f32_e32 v60, v39, v39
	v_fmac_f32_e32 v60, v40, v40
	v_fmac_f32_e32 v60, v41, v41
	v_mul_f32_e32 v61, v42, v42
	v_fmac_f32_e32 v61, v43, v43
	v_fmac_f32_e32 v61, v44, v44
	v_fmac_f32_e32 v61, v45, v45
	v_fmac_f32_e32 v61, v46, v46
	v_fmac_f32_e32 v61, v47, v47
	v_fmac_f32_e32 v61, v48, v48
	v_fmac_f32_e32 v61, v49, v49
	v_fmac_f32_e32 v61, v50, v50
	v_fmac_f32_e32 v61, v51, v51
	v_fmac_f32_e32 v61, v52, v52
	v_fmac_f32_e32 v61, v53, v53
	v_fmac_f32_e32 v61, v54, v54
	v_fmac_f32_e32 v61, v55, v55
	v_fmac_f32_e32 v61, v56, v56
	v_fmac_f32_e32 v61, v57, v57
	v_lshlrev_b32_e32 v70, 2, v210
	v_xor_b32_e32 v70, 0x80, v70
	ds_swizzle_b32 v63, v61 offset:swizzle(SWAP,16)
	ds_swizzle_b32 v62, v60 offset:swizzle(SWAP,16)
	s_waitcnt lgkmcnt(0)
	v_pk_add_f32 v[60:61], v[60:61], v[62:63]
	ds_swizzle_b32 v63, v61 offset:swizzle(SWAP,8)
	ds_swizzle_b32 v62, v60 offset:swizzle(SWAP,8)
	s_waitcnt lgkmcnt(0)
	v_pk_add_f32 v[60:61], v[60:61], v[62:63]
	ds_swizzle_b32 v63, v61 offset:swizzle(SWAP,4)
	ds_swizzle_b32 v62, v60 offset:swizzle(SWAP,4)
	s_waitcnt lgkmcnt(0)
	v_pk_add_f32 v[60:61], v[60:61], v[62:63]
	ds_swizzle_b32 v63, v61 offset:swizzle(SWAP,2)
	ds_swizzle_b32 v62, v60 offset:swizzle(SWAP,2)
	s_waitcnt lgkmcnt(0)
	v_pk_add_f32 v[60:61], v[60:61], v[62:63]
	ds_swizzle_b32 v63, v61 offset:swizzle(SWAP,1)
	ds_swizzle_b32 v62, v60 offset:swizzle(SWAP,1)
	s_waitcnt lgkmcnt(0)
	v_pk_add_f32 v[60:61], v[60:61], v[62:63]
	ds_bpermute_b32 v63, v70, v61
	ds_bpermute_b32 v62, v70, v60
	s_waitcnt lgkmcnt(0)
	v_pk_add_f32 v[60:61], v[60:61], v[62:63]
	s_nop 0
	v_pk_fma_f32 v[60:61], v[60:61], s[58:59], v[154:155] op_sel_hi:[1,0,0]
	s_nop 0
	v_rsq_f32_e32 v60, v60
	v_rsq_f32_e32 v62, v61
	s_nop 0
	v_pk_mul_f32 v[26:27], v[26:27], v[60:61] op_sel_hi:[1,0]
	v_pk_mul_f32 v[26:27], v[2:3], v[26:27]
	v_pk_mul_f32 v[28:29], v[28:29], v[60:61] op_sel_hi:[1,0]
	v_pk_mul_f32 v[28:29], v[4:5], v[28:29]
	v_pk_mul_f32 v[30:31], v[30:31], v[60:61] op_sel_hi:[1,0]
	v_pk_mul_f32 v[30:31], v[6:7], v[30:31]
	v_pk_mul_f32 v[32:33], v[32:33], v[60:61] op_sel_hi:[1,0]
	v_pk_mul_f32 v[32:33], v[8:9], v[32:33]
	v_pk_mul_f32 v[34:35], v[34:35], v[60:61] op_sel_hi:[1,0]
	v_pk_mul_f32 v[34:35], v[10:11], v[34:35]
	v_pk_mul_f32 v[36:37], v[36:37], v[60:61] op_sel_hi:[1,0]
	v_pk_mul_f32 v[36:37], v[12:13], v[36:37]
	v_pk_mul_f32 v[38:39], v[38:39], v[60:61] op_sel_hi:[1,0]
	v_pk_mul_f32 v[38:39], v[14:15], v[38:39]
	v_pk_mul_f32 v[40:41], v[40:41], v[60:61] op_sel_hi:[1,0]
	v_pk_mul_f32 v[40:41], v[16:17], v[40:41]
	v_pk_mul_f32 v[42:43], v[42:43], v[62:63] op_sel_hi:[1,0]
	v_pk_mul_f32 v[42:43], v[2:3], v[42:43]
	v_pk_mul_f32 v[44:45], v[44:45], v[62:63] op_sel_hi:[1,0]
	v_pk_mul_f32 v[44:45], v[4:5], v[44:45]
	v_pk_mul_f32 v[46:47], v[46:47], v[62:63] op_sel_hi:[1,0]
	v_pk_mul_f32 v[46:47], v[6:7], v[46:47]
	v_pk_mul_f32 v[48:49], v[48:49], v[62:63] op_sel_hi:[1,0]
	v_pk_mul_f32 v[48:49], v[8:9], v[48:49]
	v_pk_mul_f32 v[50:51], v[50:51], v[62:63] op_sel_hi:[1,0]
	v_pk_mul_f32 v[50:51], v[10:11], v[50:51]
	v_pk_mul_f32 v[52:53], v[52:53], v[62:63] op_sel_hi:[1,0]
	v_pk_mul_f32 v[52:53], v[12:13], v[52:53]
	v_pk_mul_f32 v[54:55], v[54:55], v[62:63] op_sel_hi:[1,0]
	v_pk_mul_f32 v[54:55], v[14:15], v[54:55]
	v_pk_mul_f32 v[56:57], v[56:57], v[62:63] op_sel_hi:[1,0]
	v_pk_mul_f32 v[56:57], v[16:17], v[56:57]
	v_cvt_pk_bf16_f32 v26, v26, v27
	v_cvt_pk_bf16_f32 v27, v28, v29
	v_cvt_pk_bf16_f32 v30, v30, v31
	v_cvt_pk_bf16_f32 v31, v32, v33
	v_cvt_pk_bf16_f32 v34, v34, v35
	v_cvt_pk_bf16_f32 v35, v36, v37
	v_cvt_pk_bf16_f32 v38, v38, v39
	v_cvt_pk_bf16_f32 v39, v40, v41
	global_store_dwordx2 v[24:25], v[26:27], off sc1
	global_store_dwordx2 v[24:25], v[30:31], off offset:512 sc1
	global_store_dwordx2 v[24:25], v[34:35], off offset:1024 sc1
	global_store_dwordx2 v[24:25], v[38:39], off offset:1536 sc1
	v_cvt_pk_bf16_f32 v42, v42, v43
	v_cvt_pk_bf16_f32 v43, v44, v45
	v_cvt_pk_bf16_f32 v46, v46, v47
	v_cvt_pk_bf16_f32 v47, v48, v49
	v_cvt_pk_bf16_f32 v50, v50, v51
	v_cvt_pk_bf16_f32 v51, v52, v53
	v_cvt_pk_bf16_f32 v54, v54, v55
	v_cvt_pk_bf16_f32 v55, v56, v57
	global_store_dwordx2 v[58:59], v[42:43], off sc1
	global_store_dwordx2 v[58:59], v[46:47], off offset:512 sc1
	global_store_dwordx2 v[58:59], v[50:51], off offset:1024 sc1
	global_store_dwordx2 v[58:59], v[54:55], off offset:1536 sc1

; __device__ __forceinline__ void store8bf(bf16_t* p, f32x4 v0, f32x4 v1) { u32x4 w; w.x = cvt_pk_bf16(v0[0], v0[1]); w.y = cvt_pk_bf16(v0[2], v0[3]); w.z = cvt_pk_bf16(v1[0], v1[1]); w.w = cvt_pk_bf16(v1[2], v1[3]); *(u32x4*)p = w; }
; __device__ __forceinline__ void norm_phase(const float* H, const float* g, bf16_t* HN) {
;     ...
;   for (int row = gw; row < NREAL + 64; row += 2 * nw) {
;     const int row2 = row + nw < NREAL + 64 ? row + nw : row;
;     const float* p = H + (size_t)row * DM + lane * 8; const float* p2 = H + (size_t)row2 * DM + lane * 8; f32x4 v[4], u[4]; float ss = 0.f, ss2 = 0.f;
; #pragma unroll
;     for (int i = 0; i < 4; ++i) { v[i] = *(const f32x4*)(p + 512 * (i >> 1) + 4 * (i & 1)); u[i] = *(const f32x4*)(p2 + 512 * (i >> 1) + 4 * (i & 1)); }
; #pragma unroll
;     for (int i = 0; i < 4; ++i) { ss += v[i][0] * v[i][0] + v[i][1] * v[i][1] + v[i][2] * v[i][2] + v[i][3] * v[i][3]; ss2 += u[i][0] * u[i][0] + u[i][1] * u[i][1] + u[i][2] * u[i][2] + u[i][3] * u[i][3]; }
;     ss = wave_sum(ss); ss2 = wave_sum(ss2); const float rs = rsqrtf(ss * (1.0f / 1024.0f) + 1e-6f), rs2 = rsqrtf(ss2 * (1.0f / 1024.0f) + 1e-6f);
;     bf16_t* q = HN + (size_t)row * DM + lane * 8; bf16_t* q2 = HN + (size_t)row2 * DM + lane * 8;
; #pragma unroll
;     for (int i = 0; i < 2; ++i) { store8bf(q + 512 * i, v[2 * i] * rs * gv[2 * i], v[2 * i + 1] * rs * gv[2 * i + 1]); store8bf(q2 + 512 * i, u[2 * i] * rs2 * gv[2 * i], u[2 * i + 1] * rs2 * gv[2 * i + 1]); }
;   }
.LBB0_1501:
	v_readfirstlane_b32 s0, v54
	s_nop 3
	s_add_i32 s9, s0, s24
	s_cmp_lt_i32 s9, s49
	s_cselect_b32 s9, s9, s0
	s_lshl_b32 s10, s0, 12
	s_lshl_b32 s4, s9, 12
	v_mov_b32_e32 v62, s10
	v_mov_b32_e32 v63, 0
	v_lshl_add_u64 v[64:65], v[50:51], 0, v[62:63]
	v_mov_b32_e32 v62, s4
	v_lshl_add_u64 v[66:67], v[50:51], 0, v[62:63]
	global_load_dwordx4 v[18:21], v[64:65], off
	global_load_dwordx4 v[22:25], v[64:65], off offset:1024
	global_load_dwordx4 v[26:29], v[64:65], off offset:2048
	global_load_dwordx4 v[30:33], v[64:65], off offset:3072
	global_load_dwordx4 v[34:37], v[66:67], off
	global_load_dwordx4 v[38:41], v[66:67], off offset:1024
	global_load_dwordx4 v[42:45], v[66:67], off offset:2048
	global_load_dwordx4 v[46:49], v[66:67], off offset:3072
	s_lshl_b32 s10, s0, 11
	s_lshl_b32 s4, s9, 11
	v_mov_b32_e32 v62, s10
	v_lshl_add_u64 v[54:55], v[52:53], 0, v[62:63]
	v_mov_b32_e32 v62, s4
	v_lshl_add_u64 v[56:57], v[52:53], 0, v[62:63]
	s_lshl_b32 s8, s24, 1
	s_add_i32 s1, s0, s8
	s_cmp_lt_i32 s1, s49
	s_cbranch_scc0 .Ln2_lastA_first
	s_add_i32 s9, s1, s24
	s_cmp_lt_i32 s9, s49
	s_cselect_b32 s9, s9, s1
	s_lshl_b32 s10, s1, 12
	s_lshl_b32 s4, s9, 12
	v_mov_b32_e32 v62, s10
	v_mov_b32_e32 v63, 0
	v_lshl_add_u64 v[64:65], v[50:51], 0, v[62:63]
	v_mov_b32_e32 v62, s4
	v_lshl_add_u64 v[66:67], v[50:51], 0, v[62:63]
	global_load_dwordx4 v[70:73], v[64:65], off
	global_load_dwordx4 v[74:77], v[64:65], off offset:1024
	global_load_dwordx4 v[78:81], v[64:65], off offset:2048
	global_load_dwordx4 v[82:85], v[64:65], off offset:3072
	global_load_dwordx4 v[88:91], v[66:67], off
	global_load_dwordx4 v[92:95], v[66:67], off offset:1024
	global_load_dwordx4 v[96:99], v[66:67], off offset:2048
	global_load_dwordx4 v[100:103], v[66:67], off offset:3072
	s_lshl_b32 s10, s1, 11
	s_lshl_b32 s4, s9, 11
	v_mov_b32_e32 v62, s10
	v_lshl_add_u64 v[128:129], v[52:53], 0, v[62:63]
	v_mov_b32_e32 v62, s4
	v_lshl_add_u64 v[130:131], v[52:53], 0, v[62:63]
	s_waitcnt vmcnt(8)
	v_mul_f32_e32 v58, v18, v18
	v_fmac_f32_e32 v58, v19, v19
	v_fmac_f32_e32 v58, v20, v20
	v_fmac_f32_e32 v58, v21, v21
	v_fmac_f32_e32 v58, v22, v22
	v_fmac_f32_e32 v58, v23, v23
	v_fmac_f32_e32 v58, v24, v24
	v_fmac_f32_e32 v58, v25, v25
	v_fmac_f32_e32 v58, v26, v26
	v_fmac_f32_e32 v58, v27, v27
	v_fmac_f32_e32 v58, v28, v28
	v_fmac_f32_e32 v58, v29, v29
	v_fmac_f32_e32 v58, v30, v30
	v_fmac_f32_e32 v58, v31, v31
	v_fmac_f32_e32 v58, v32, v32
	v_fmac_f32_e32 v58, v33, v33
	v_mul_f32_e32 v59, v34, v34
	v_fmac_f32_e32 v59, v35, v35
	v_fmac_f32_e32 v59, v36, v36
	v_fmac_f32_e32 v59, v37, v37
	v_fmac_f32_e32 v59, v38, v38
	v_fmac_f32_e32 v59, v39, v39
	v_fmac_f32_e32 v59, v40, v40
	v_fmac_f32_e32 v59, v41, v41
	v_fmac_f32_e32 v59, v42, v42
	v_fmac_f32_e32 v59, v43, v43
	v_fmac_f32_e32 v59, v44, v44
	v_fmac_f32_e32 v59, v45, v45
	v_fmac_f32_e32 v59, v46, v46
	v_fmac_f32_e32 v59, v47, v47
	v_fmac_f32_e32 v59, v48, v48
	v_fmac_f32_e32 v59, v49, v49
	v_lshlrev_b32_e32 v68, 2, v210
	v_xor_b32_e32 v68, 0x80, v68
	ds_swizzle_b32 v61, v59 offset:swizzle(SWAP,16)
	ds_swizzle_b32 v60, v58 offset:swizzle(SWAP,16)
	s_waitcnt lgkmcnt(0)
	v_pk_add_f32 v[58:59], v[58:59], v[60:61]
	ds_swizzle_b32 v61, v59 offset:swizzle(SWAP,8)
	ds_swizzle_b32 v60, v58 offset:swizzle(SWAP,8)
	s_waitcnt lgkmcnt(0)
	v_pk_add_f32 v[58:59], v[58:59], v[60:61]
	ds_swizzle_b32 v61, v59 offset:swizzle(SWAP,4)
	ds_swizzle_b32 v60, v58 offset:swizzle(SWAP,4)
	s_waitcnt lgkmcnt(0)
	v_pk_add_f32 v[58:59], v[58:59], v[60:61]
	ds_swizzle_b32 v61, v59 offset:swizzle(SWAP,2)
	ds_swizzle_b32 v60, v58 offset:swizzle(SWAP,2)
	s_waitcnt lgkmcnt(0)
	v_pk_add_f32 v[58:59], v[58:59], v[60:61]
	ds_swizzle_b32 v61, v59 offset:swizzle(SWAP,1)
	ds_swizzle_b32 v60, v58 offset:swizzle(SWAP,1)
	s_waitcnt lgkmcnt(0)
	v_pk_add_f32 v[58:59], v[58:59], v[60:61]
	ds_bpermute_b32 v61, v68, v59
	ds_bpermute_b32 v60, v68, v58
	s_waitcnt lgkmcnt(0)
	v_pk_add_f32 v[58:59], v[58:59], v[60:61]
	s_nop 0
	v_pk_fma_f32 v[58:59], v[58:59], s[58:59], v[154:155] op_sel_hi:[1,0,0]
	s_nop 0
	v_rsq_f32_e32 v58, v58
	v_rsq_f32_e32 v60, v59
	s_nop 0
	v_pk_mul_f32 v[18:19], v[18:19], v[58:59] op_sel_hi:[1,0]
	v_pk_mul_f32 v[18:19], v[2:3], v[18:19]
	v_pk_mul_f32 v[20:21], v[20:21], v[58:59] op_sel_hi:[1,0]
	v_pk_mul_f32 v[20:21], v[4:5], v[20:21]
	v_pk_mul_f32 v[22:23], v[22:23], v[58:59] op_sel_hi:[1,0]
	v_pk_mul_f32 v[22:23], v[6:7], v[22:23]
	v_pk_mul_f32 v[24:25], v[24:25], v[58:59] op_sel_hi:[1,0]
	v_pk_mul_f32 v[24:25], v[8:9], v[24:25]
	v_pk_mul_f32 v[26:27], v[26:27], v[58:59] op_sel_hi:[1,0]
	v_pk_mul_f32 v[26:27], v[10:11], v[26:27]
	v_pk_mul_f32 v[28:29], v[28:29], v[58:59] op_sel_hi:[1,0]
	v_pk_mul_f32 v[28:29], v[12:13], v[28:29]
	v_pk_mul_f32 v[30:31], v[30:31], v[58:59] op_sel_hi:[1,0]
	v_pk_mul_f32 v[30:31], v[14:15], v[30:31]
	v_pk_mul_f32 v[32:33], v[32:33], v[58:59] op_sel_hi:[1,0]
	v_pk_mul_f32 v[32:33], v[16:17], v[32:33]
	v_pk_mul_f32 v[34:35], v[34:35], v[60:61] op_sel_hi:[1,0]
	v_pk_mul_f32 v[34:35], v[2:3], v[34:35]
	v_pk_mul_f32 v[36:37], v[36:37], v[60:61] op_sel_hi:[1,0]
	v_pk_mul_f32 v[36:37], v[4:5], v[36:37]
	v_pk_mul_f32 v[38:39], v[38:39], v[60:61] op_sel_hi:[1,0]
	v_pk_mul_f32 v[38:39], v[6:7], v[38:39]
	v_pk_mul_f32 v[40:41], v[40:41], v[60:61] op_sel_hi:[1,0]
	v_pk_mul_f32 v[40:41], v[8:9], v[40:41]
	v_pk_mul_f32 v[42:43], v[42:43], v[60:61] op_sel_hi:[1,0]
	v_pk_mul_f32 v[42:43], v[10:11], v[42:43]
	v_pk_mul_f32 v[44:45], v[44:45], v[60:61] op_sel_hi:[1,0]
	v_pk_mul_f32 v[44:45], v[12:13], v[44:45]
	v_pk_mul_f32 v[46:47], v[46:47], v[60:61] op_sel_hi:[1,0]
	v_pk_mul_f32 v[46:47], v[14:15], v[46:47]
	v_pk_mul_f32 v[48:49], v[48:49], v[60:61] op_sel_hi:[1,0]
	v_pk_mul_f32 v[48:49], v[16:17], v[48:49]
	v_cvt_pk_bf16_f32 v18, v18, v19
	v_cvt_pk_bf16_f32 v19, v20, v21
	v_cvt_pk_bf16_f32 v22, v22, v23
	v_cvt_pk_bf16_f32 v23, v24, v25
	v_cvt_pk_bf16_f32 v26, v26, v27
	v_cvt_pk_bf16_f32 v27, v28, v29
	v_cvt_pk_bf16_f32 v30, v30, v31
	v_cvt_pk_bf16_f32 v31, v32, v33
	global_store_dwordx2 v[54:55], v[18:19], off sc1
	global_store_dwordx2 v[54:55], v[22:23], off offset:512 sc1
	global_store_dwordx2 v[54:55], v[26:27], off offset:1024 sc1
	global_store_dwordx2 v[54:55], v[30:31], off offset:1536 sc1
	v_cvt_pk_bf16_f32 v34, v34, v35
	v_cvt_pk_bf16_f32 v35, v36, v37
	v_cvt_pk_bf16_f32 v38, v38, v39
	v_cvt_pk_bf16_f32 v39, v40, v41
	v_cvt_pk_bf16_f32 v42, v42, v43
	v_cvt_pk_bf16_f32 v43, v44, v45
	v_cvt_pk_bf16_f32 v46, v46, v47
	v_cvt_pk_bf16_f32 v47, v48, v49
	global_store_dwordx2 v[56:57], v[34:35], off sc1
	global_store_dwordx2 v[56:57], v[38:39], off offset:512 sc1
	global_store_dwordx2 v[56:57], v[42:43], off offset:1024 sc1
	global_store_dwordx2 v[56:57], v[46:47], off offset:1536 sc1
; __device__ __forceinline__ void store8bf(bf16_t* p, f32x4 v0, f32x4 v1) { u32x4 w; w.x = cvt_pk_bf16(v0[0], v0[1]); w.y = cvt_pk_bf16(v0[2], v0[3]); w.z = cvt_pk_bf16(v1[0], v1[1]); w.w = cvt_pk_bf16(v1[2], v1[3]); *(u32x4*)p = w; }
; __device__ __forceinline__ void norm_phase(const float* H, const float* g, bf16_t* HN) {
;     ...
;   for (int row = gw; row < NREAL + 64; row += 2 * nw) {
;     const int row2 = row + nw < NREAL + 64 ? row + nw : row;
;     const float* p = H + (size_t)row * DM + lane * 8; const float* p2 = H + (size_t)row2 * DM + lane * 8; f32x4 v[4], u[4]; float ss = 0.f, ss2 = 0.f;
; #pragma unroll
;     for (int i = 0; i < 4; ++i) { v[i] = *(const f32x4*)(p + 512 * (i >> 1) + 4 * (i & 1)); u[i] = *(const f32x4*)(p2 + 512 * (i >> 1) + 4 * (i & 1)); }
; #pragma unroll
;     for (int i = 0; i < 4; ++i) { ss += v[i][0] * v[i][0] + v[i][1] * v[i][1] + v[i][2] * v[i][2] + v[i][3] * v[i][3]; ss2 += u[i][0] * u[i][0] + u[i][1] * u[i][1] + u[i][2] * u[i][2] + u[i][3] * u[i][3]; }
;     ss = wave_sum(ss); ss2 = wave_sum(ss2); const float rs = rsqrtf(ss * (1.0f / 1024.0f) + 1e-6f), rs2 = rsqrtf(ss2 * (1.0f / 1024.0f) + 1e-6f);
;     bf16_t* q = HN + (size_t)row * DM + lane * 8; bf16_t* q2 = HN + (size_t)row2 * DM + lane * 8;
; #pragma unroll
;     for (int i = 0; i < 2; ++i) { store8bf(q + 512 * i, v[2 * i] * rs * gv[2 * i], v[2 * i + 1] * rs * gv[2 * i + 1]); store8bf(q2 + 512 * i, u[2 * i] * rs2 * gv[2 * i], u[2 * i + 1] * rs2 * gv[2 * i + 1]); }
;   }
.Ln2_loop:
	s_add_i32 s0, s1, s8
	s_cmp_lt_i32 s0, s49
	s_cbranch_scc0 .Ln2_lastB
	s_add_i32 s9, s0, s24
	s_cmp_lt_i32 s9, s49
	s_cselect_b32 s9, s9, s0
	s_lshl_b32 s10, s0, 12
	s_lshl_b32 s4, s9, 12
	v_mov_b32_e32 v62, s10
	v_mov_b32_e32 v63, 0
	v_lshl_add_u64 v[64:65], v[50:51], 0, v[62:63]
	v_mov_b32_e32 v62, s4
	v_lshl_add_u64 v[66:67], v[50:51], 0, v[62:63]
	global_load_dwordx4 v[18:21], v[64:65], off
	global_load_dwordx4 v[22:25], v[64:65], off offset:1024
	global_load_dwordx4 v[26:29], v[64:65], off offset:2048
	global_load_dwordx4 v[30:33], v[64:65], off offset:3072
	global_load_dwordx4 v[34:37], v[66:67], off
	global_load_dwordx4 v[38:41], v[66:67], off offset:1024
	global_load_dwordx4 v[42:45], v[66:67], off offset:2048
	global_load_dwordx4 v[46:49], v[66:67], off offset:3072
	s_lshl_b32 s10, s0, 11
	s_lshl_b32 s4, s9, 11
	v_mov_b32_e32 v62, s10
	v_lshl_add_u64 v[54:55], v[52:53], 0, v[62:63]
	v_mov_b32_e32 v62, s4
	v_lshl_add_u64 v[56:57], v[52:53], 0, v[62:63]
	s_waitcnt vmcnt(16)
	v_mul_f32_e32 v58, v70, v70
	v_fmac_f32_e32 v58, v71, v71
	v_fmac_f32_e32 v58, v72, v72
	v_fmac_f32_e32 v58, v73, v73
	v_fmac_f32_e32 v58, v74, v74
	v_fmac_f32_e32 v58, v75, v75
	v_fmac_f32_e32 v58, v76, v76
	v_fmac_f32_e32 v58, v77, v77
	v_fmac_f32_e32 v58, v78, v78
	v_fmac_f32_e32 v58, v79, v79
	v_fmac_f32_e32 v58, v80, v80
	v_fmac_f32_e32 v58, v81, v81
	v_fmac_f32_e32 v58, v82, v82
	v_fmac_f32_e32 v58, v83, v83
	v_fmac_f32_e32 v58, v84, v84
	v_fmac_f32_e32 v58, v85, v85
	v_mul_f32_e32 v59, v88, v88
	v_fmac_f32_e32 v59, v89, v89
	v_fmac_f32_e32 v59, v90, v90
	v_fmac_f32_e32 v59, v91, v91
	v_fmac_f32_e32 v59, v92, v92
	v_fmac_f32_e32 v59, v93, v93
	v_fmac_f32_e32 v59, v94, v94
	v_fmac_f32_e32 v59, v95, v95
	v_fmac_f32_e32 v59, v96, v96
	v_fmac_f32_e32 v59, v97, v97
	v_fmac_f32_e32 v59, v98, v98
	v_fmac_f32_e32 v59, v99, v99
	v_fmac_f32_e32 v59, v100, v100
	v_fmac_f32_e32 v59, v101, v101
	v_fmac_f32_e32 v59, v102, v102
	v_fmac_f32_e32 v59, v103, v103
	v_lshlrev_b32_e32 v68, 2, v210
	v_xor_b32_e32 v68, 0x80, v68
	ds_swizzle_b32 v61, v59 offset:swizzle(SWAP,16)
	ds_swizzle_b32 v60, v58 offset:swizzle(SWAP,16)
	s_waitcnt lgkmcnt(0)
	v_pk_add_f32 v[58:59], v[58:59], v[60:61]
	ds_swizzle_b32 v61, v59 offset:swizzle(SWAP,8)
	ds_swizzle_b32 v60, v58 offset:swizzle(SWAP,8)
	s_waitcnt lgkmcnt(0)
	v_pk_add_f32 v[58:59], v[58:59], v[60:61]
	ds_swizzle_b32 v61, v59 offset:swizzle(SWAP,4)
	ds_swizzle_b32 v60, v58 offset:swizzle(SWAP,4)
	s_waitcnt lgkmcnt(0)
	v_pk_add_f32 v[58:59], v[58:59], v[60:61]
	ds_swizzle_b32 v61, v59 offset:swizzle(SWAP,2)
	ds_swizzle_b32 v60, v58 offset:swizzle(SWAP,2)
	s_waitcnt lgkmcnt(0)
	v_pk_add_f32 v[58:59], v[58:59], v[60:61]
	ds_swizzle_b32 v61, v59 offset:swizzle(SWAP,1)
	ds_swizzle_b32 v60, v58 offset:swizzle(SWAP,1)
	s_waitcnt lgkmcnt(0)
	v_pk_add_f32 v[58:59], v[58:59], v[60:61]
	ds_bpermute_b32 v61, v68, v59
	ds_bpermute_b32 v60, v68, v58
	s_waitcnt lgkmcnt(0)
	v_pk_add_f32 v[58:59], v[58:59], v[60:61]
	s_nop 0
	v_pk_fma_f32 v[58:59], v[58:59], s[58:59], v[154:155] op_sel_hi:[1,0,0]
	s_nop 0
	v_rsq_f32_e32 v58, v58
	v_rsq_f32_e32 v60, v59
	s_nop 0
	v_pk_mul_f32 v[70:71], v[70:71], v[58:59] op_sel_hi:[1,0]
	v_pk_mul_f32 v[70:71], v[2:3], v[70:71]
	v_pk_mul_f32 v[72:73], v[72:73], v[58:59] op_sel_hi:[1,0]
	v_pk_mul_f32 v[72:73], v[4:5], v[72:73]
	v_pk_mul_f32 v[74:75], v[74:75], v[58:59] op_sel_hi:[1,0]
	v_pk_mul_f32 v[74:75], v[6:7], v[74:75]
	v_pk_mul_f32 v[76:77], v[76:77], v[58:59] op_sel_hi:[1,0]
	v_pk_mul_f32 v[76:77], v[8:9], v[76:77]
	v_pk_mul_f32 v[78:79], v[78:79], v[58:59] op_sel_hi:[1,0]
	v_pk_mul_f32 v[78:79], v[10:11], v[78:79]
	v_pk_mul_f32 v[80:81], v[80:81], v[58:59] op_sel_hi:[1,0]
	v_pk_mul_f32 v[80:81], v[12:13], v[80:81]
	v_pk_mul_f32 v[82:83], v[82:83], v[58:59] op_sel_hi:[1,0]
	v_pk_mul_f32 v[82:83], v[14:15], v[82:83]
	v_pk_mul_f32 v[84:85], v[84:85], v[58:59] op_sel_hi:[1,0]
	v_pk_mul_f32 v[84:85], v[16:17], v[84:85]
	v_pk_mul_f32 v[88:89], v[88:89], v[60:61] op_sel_hi:[1,0]
	v_pk_mul_f32 v[88:89], v[2:3], v[88:89]
	v_pk_mul_f32 v[90:91], v[90:91], v[60:61] op_sel_hi:[1,0]
	v_pk_mul_f32 v[90:91], v[4:5], v[90:91]
	v_pk_mul_f32 v[92:93], v[92:93], v[60:61] op_sel_hi:[1,0]
	v_pk_mul_f32 v[92:93], v[6:7], v[92:93]
	v_pk_mul_f32 v[94:95], v[94:95], v[60:61] op_sel_hi:[1,0]
	v_pk_mul_f32 v[94:95], v[8:9], v[94:95]
	v_pk_mul_f32 v[96:97], v[96:97], v[60:61] op_sel_hi:[1,0]
	v_pk_mul_f32 v[96:97], v[10:11], v[96:97]
	v_pk_mul_f32 v[98:99], v[98:99], v[60:61] op_sel_hi:[1,0]
	v_pk_mul_f32 v[98:99], v[12:13], v[98:99]
	v_pk_mul_f32 v[100:101], v[100:101], v[60:61] op_sel_hi:[1,0]
	v_pk_mul_f32 v[100:101], v[14:15], v[100:101]
	v_pk_mul_f32 v[102:103], v[102:103], v[60:61] op_sel_hi:[1,0]
	v_pk_mul_f32 v[102:103], v[16:17], v[102:103]
	v_cvt_pk_bf16_f32 v70, v70, v71
	v_cvt_pk_bf16_f32 v71, v72, v73
	v_cvt_pk_bf16_f32 v74, v74, v75
	v_cvt_pk_bf16_f32 v75, v76, v77
	v_cvt_pk_bf16_f32 v78, v78, v79
	v_cvt_pk_bf16_f32 v79, v80, v81
	v_cvt_pk_bf16_f32 v82, v82, v83
	v_cvt_pk_bf16_f32 v83, v84, v85
	global_store_dwordx2 v[128:129], v[70:71], off sc1
	global_store_dwordx2 v[128:129], v[74:75], off offset:512 sc1
	global_store_dwordx2 v[128:129], v[78:79], off offset:1024 sc1
	global_store_dwordx2 v[128:129], v[82:83], off offset:1536 sc1
	v_cvt_pk_bf16_f32 v88, v88, v89
	v_cvt_pk_bf16_f32 v89, v90, v91
	v_cvt_pk_bf16_f32 v92, v92, v93
	v_cvt_pk_bf16_f32 v93, v94, v95
	v_cvt_pk_bf16_f32 v96, v96, v97
	v_cvt_pk_bf16_f32 v97, v98, v99
	v_cvt_pk_bf16_f32 v100, v100, v101
	v_cvt_pk_bf16_f32 v101, v102, v103
	global_store_dwordx2 v[130:131], v[88:89], off sc1
	global_store_dwordx2 v[130:131], v[92:93], off offset:512 sc1
	global_store_dwordx2 v[130:131], v[96:97], off offset:1024 sc1
	global_store_dwordx2 v[130:131], v[100:101], off offset:1536 sc1
	s_add_i32 s1, s0, s8
	s_cmp_lt_i32 s1, s49
	s_cbranch_scc0 .Ln2_lastA
; __device__ __forceinline__ void store8bf(bf16_t* p, f32x4 v0, f32x4 v1) { u32x4 w; w.x = cvt_pk_bf16(v0[0], v0[1]); w.y = cvt_pk_bf16(v0[2], v0[3]); w.z = cvt_pk_bf16(v1[0], v1[1]); w.w = cvt_pk_bf16(v1[2], v1[3]); *(u32x4*)p = w; }
; __device__ __forceinline__ void norm_phase(const float* H, const float* g, bf16_t* HN) {
;     ...
;   for (int row = gw; row < NREAL + 64; row += 2 * nw) {
;     const int row2 = row + nw < NREAL + 64 ? row + nw : row;
;     const float* p = H + (size_t)row * DM + lane * 8; const float* p2 = H + (size_t)row2 * DM + lane * 8; f32x4 v[4], u[4]; float ss = 0.f, ss2 = 0.f;
; #pragma unroll
;     for (int i = 0; i < 4; ++i) { v[i] = *(const f32x4*)(p + 512 * (i >> 1) + 4 * (i & 1)); u[i] = *(const f32x4*)(p2 + 512 * (i >> 1) + 4 * (i & 1)); }
; #pragma unroll
;     for (int i = 0; i < 4; ++i) { ss += v[i][0] * v[i][0] + v[i][1] * v[i][1] + v[i][2] * v[i][2] + v[i][3] * v[i][3]; ss2 += u[i][0] * u[i][0] + u[i][1] * u[i][1] + u[i][2] * u[i][2] + u[i][3] * u[i][3]; }
;     ss = wave_sum(ss); ss2 = wave_sum(ss2); const float rs = rsqrtf(ss * (1.0f / 1024.0f) + 1e-6f), rs2 = rsqrtf(ss2 * (1.0f / 1024.0f) + 1e-6f);
;     bf16_t* q = HN + (size_t)row * DM + lane * 8; bf16_t* q2 = HN + (size_t)row2 * DM + lane * 8;
; #pragma unroll
;     for (int i = 0; i < 2; ++i) { store8bf(q + 512 * i, v[2 * i] * rs * gv[2 * i], v[2 * i + 1] * rs * gv[2 * i + 1]); store8bf(q2 + 512 * i, u[2 * i] * rs2 * gv[2 * i], u[2 * i + 1] * rs2 * gv[2 * i + 1]); }
;   }
	s_add_i32 s9, s1, s24
	s_cmp_lt_i32 s9, s49
	s_cselect_b32 s9, s9, s1
	s_lshl_b32 s10, s1, 12
	s_lshl_b32 s4, s9, 12
	v_mov_b32_e32 v62, s10
	v_mov_b32_e32 v63, 0
	v_lshl_add_u64 v[64:65], v[50:51], 0, v[62:63]
	v_mov_b32_e32 v62, s4
	v_lshl_add_u64 v[66:67], v[50:51], 0, v[62:63]
	global_load_dwordx4 v[70:73], v[64:65], off
	global_load_dwordx4 v[74:77], v[64:65], off offset:1024
	global_load_dwordx4 v[78:81], v[64:65], off offset:2048
	global_load_dwordx4 v[82:85], v[64:65], off offset:3072
	global_load_dwordx4 v[88:91], v[66:67], off
	global_load_dwordx4 v[92:95], v[66:67], off offset:1024
	global_load_dwordx4 v[96:99], v[66:67], off offset:2048
	global_load_dwordx4 v[100:103], v[66:67], off offset:3072
	s_lshl_b32 s10, s1, 11
	s_lshl_b32 s4, s9, 11
	v_mov_b32_e32 v62, s10
	v_lshl_add_u64 v[128:129], v[52:53], 0, v[62:63]
	v_mov_b32_e32 v62, s4
	v_lshl_add_u64 v[130:131], v[52:53], 0, v[62:63]
	s_waitcnt vmcnt(16)
	v_mul_f32_e32 v58, v18, v18
	v_fmac_f32_e32 v58, v19, v19
	v_fmac_f32_e32 v58, v20, v20
	v_fmac_f32_e32 v58, v21, v21
	v_fmac_f32_e32 v58, v22, v22
	v_fmac_f32_e32 v58, v23, v23
	v_fmac_f32_e32 v58, v24, v24
	v_fmac_f32_e32 v58, v25, v25
	v_fmac_f32_e32 v58, v26, v26
	v_fmac_f32_e32 v58, v27, v27
	v_fmac_f32_e32 v58, v28, v28
	v_fmac_f32_e32 v58, v29, v29
	v_fmac_f32_e32 v58, v30, v30
	v_fmac_f32_e32 v58, v31, v31
	v_fmac_f32_e32 v58, v32, v32
	v_fmac_f32_e32 v58, v33, v33
	v_mul_f32_e32 v59, v34, v34
	v_fmac_f32_e32 v59, v35, v35
	v_fmac_f32_e32 v59, v36, v36
	v_fmac_f32_e32 v59, v37, v37
	v_fmac_f32_e32 v59, v38, v38
	v_fmac_f32_e32 v59, v39, v39
	v_fmac_f32_e32 v59, v40, v40
	v_fmac_f32_e32 v59, v41, v41
	v_fmac_f32_e32 v59, v42, v42
	v_fmac_f32_e32 v59, v43, v43
	v_fmac_f32_e32 v59, v44, v44
	v_fmac_f32_e32 v59, v45, v45
	v_fmac_f32_e32 v59, v46, v46
	v_fmac_f32_e32 v59, v47, v47
	v_fmac_f32_e32 v59, v48, v48
	v_fmac_f32_e32 v59, v49, v49
	v_lshlrev_b32_e32 v68, 2, v210
	v_xor_b32_e32 v68, 0x80, v68
	ds_swizzle_b32 v61, v59 offset:swizzle(SWAP,16)
	ds_swizzle_b32 v60, v58 offset:swizzle(SWAP,16)
	s_waitcnt lgkmcnt(0)
	v_pk_add_f32 v[58:59], v[58:59], v[60:61]
	ds_swizzle_b32 v61, v59 offset:swizzle(SWAP,8)
	ds_swizzle_b32 v60, v58 offset:swizzle(SWAP,8)
	s_waitcnt lgkmcnt(0)
	v_pk_add_f32 v[58:59], v[58:59], v[60:61]
	ds_swizzle_b32 v61, v59 offset:swizzle(SWAP,4)
	ds_swizzle_b32 v60, v58 offset:swizzle(SWAP,4)
	s_waitcnt lgkmcnt(0)
	v_pk_add_f32 v[58:59], v[58:59], v[60:61]
	ds_swizzle_b32 v61, v59 offset:swizzle(SWAP,2)
	ds_swizzle_b32 v60, v58 offset:swizzle(SWAP,2)
	s_waitcnt lgkmcnt(0)
	v_pk_add_f32 v[58:59], v[58:59], v[60:61]
	ds_swizzle_b32 v61, v59 offset:swizzle(SWAP,1)
	ds_swizzle_b32 v60, v58 offset:swizzle(SWAP,1)
	s_waitcnt lgkmcnt(0)
	v_pk_add_f32 v[58:59], v[58:59], v[60:61]
	ds_bpermute_b32 v61, v68, v59
	ds_bpermute_b32 v60, v68, v58
	s_waitcnt lgkmcnt(0)
	v_pk_add_f32 v[58:59], v[58:59], v[60:61]
	s_nop 0
	v_pk_fma_f32 v[58:59], v[58:59], s[58:59], v[154:155] op_sel_hi:[1,0,0]
	s_nop 0
	v_rsq_f32_e32 v58, v58
	v_rsq_f32_e32 v60, v59
	s_nop 0
	v_pk_mul_f32 v[18:19], v[18:19], v[58:59] op_sel_hi:[1,0]
	v_pk_mul_f32 v[18:19], v[2:3], v[18:19]
	v_pk_mul_f32 v[20:21], v[20:21], v[58:59] op_sel_hi:[1,0]
	v_pk_mul_f32 v[20:21], v[4:5], v[20:21]
	v_pk_mul_f32 v[22:23], v[22:23], v[58:59] op_sel_hi:[1,0]
	v_pk_mul_f32 v[22:23], v[6:7], v[22:23]
	v_pk_mul_f32 v[24:25], v[24:25], v[58:59] op_sel_hi:[1,0]
	v_pk_mul_f32 v[24:25], v[8:9], v[24:25]
	v_pk_mul_f32 v[26:27], v[26:27], v[58:59] op_sel_hi:[1,0]
	v_pk_mul_f32 v[26:27], v[10:11], v[26:27]
	v_pk_mul_f32 v[28:29], v[28:29], v[58:59] op_sel_hi:[1,0]
	v_pk_mul_f32 v[28:29], v[12:13], v[28:29]
	v_pk_mul_f32 v[30:31], v[30:31], v[58:59] op_sel_hi:[1,0]
	v_pk_mul_f32 v[30:31], v[14:15], v[30:31]
	v_pk_mul_f32 v[32:33], v[32:33], v[58:59] op_sel_hi:[1,0]
	v_pk_mul_f32 v[32:33], v[16:17], v[32:33]
	v_pk_mul_f32 v[34:35], v[34:35], v[60:61] op_sel_hi:[1,0]
	v_pk_mul_f32 v[34:35], v[2:3], v[34:35]
	v_pk_mul_f32 v[36:37], v[36:37], v[60:61] op_sel_hi:[1,0]
	v_pk_mul_f32 v[36:37], v[4:5], v[36:37]
	v_pk_mul_f32 v[38:39], v[38:39], v[60:61] op_sel_hi:[1,0]
	v_pk_mul_f32 v[38:39], v[6:7], v[38:39]
	v_pk_mul_f32 v[40:41], v[40:41], v[60:61] op_sel_hi:[1,0]
	v_pk_mul_f32 v[40:41], v[8:9], v[40:41]
	v_pk_mul_f32 v[42:43], v[42:43], v[60:61] op_sel_hi:[1,0]
	v_pk_mul_f32 v[42:43], v[10:11], v[42:43]
	v_pk_mul_f32 v[44:45], v[44:45], v[60:61] op_sel_hi:[1,0]
	v_pk_mul_f32 v[44:45], v[12:13], v[44:45]
	v_pk_mul_f32 v[46:47], v[46:47], v[60:61] op_sel_hi:[1,0]
	v_pk_mul_f32 v[46:47], v[14:15], v[46:47]
	v_pk_mul_f32 v[48:49], v[48:49], v[60:61] op_sel_hi:[1,0]
	v_pk_mul_f32 v[48:49], v[16:17], v[48:49]
	v_cvt_pk_bf16_f32 v18, v18, v19
	v_cvt_pk_bf16_f32 v19, v20, v21
	v_cvt_pk_bf16_f32 v22, v22, v23
	v_cvt_pk_bf16_f32 v23, v24, v25
	v_cvt_pk_bf16_f32 v26, v26, v27
	v_cvt_pk_bf16_f32 v27, v28, v29
	v_cvt_pk_bf16_f32 v30, v30, v31
	v_cvt_pk_bf16_f32 v31, v32, v33
	global_store_dwordx2 v[54:55], v[18:19], off sc1
	global_store_dwordx2 v[54:55], v[22:23], off offset:512 sc1
	global_store_dwordx2 v[54:55], v[26:27], off offset:1024 sc1
	global_store_dwordx2 v[54:55], v[30:31], off offset:1536 sc1
	v_cvt_pk_bf16_f32 v34, v34, v35
	v_cvt_pk_bf16_f32 v35, v36, v37
	v_cvt_pk_bf16_f32 v38, v38, v39
	v_cvt_pk_bf16_f32 v39, v40, v41
	v_cvt_pk_bf16_f32 v42, v42, v43
	v_cvt_pk_bf16_f32 v43, v44, v45
	v_cvt_pk_bf16_f32 v46, v46, v47
	v_cvt_pk_bf16_f32 v47, v48, v49
	global_store_dwordx2 v[56:57], v[34:35], off sc1
	global_store_dwordx2 v[56:57], v[38:39], off offset:512 sc1
	global_store_dwordx2 v[56:57], v[42:43], off offset:1024 sc1
	global_store_dwordx2 v[56:57], v[46:47], off offset:1536 sc1
	s_branch .Ln2_loop
; __device__ __forceinline__ void store8bf(bf16_t* p, f32x4 v0, f32x4 v1) { u32x4 w; w.x = cvt_pk_bf16(v0[0], v0[1]); w.y = cvt_pk_bf16(v0[2], v0[3]); w.z = cvt_pk_bf16(v1[0], v1[1]); w.w = cvt_pk_bf16(v1[2], v1[3]); *(u32x4*)p = w; }
; __device__ __forceinline__ void norm_phase(const float* H, const float* g, bf16_t* HN) {
;     ...
;     const float* p = H + (size_t)row * DM + lane * 8; const float* p2 = H + (size_t)row2 * DM + lane * 8; f32x4 v[4], u[4]; float ss = 0.f, ss2 = 0.f;
; #pragma unroll
;     for (int i = 0; i < 4; ++i) { v[i] = *(const f32x4*)(p + 512 * (i >> 1) + 4 * (i & 1)); u[i] = *(const f32x4*)(p2 + 512 * (i >> 1) + 4 * (i & 1)); }
; #pragma unroll
;     for (int i = 0; i < 4; ++i) { ss += v[i][0] * v[i][0] + v[i][1] * v[i][1] + v[i][2] * v[i][2] + v[i][3] * v[i][3]; ss2 += u[i][0] * u[i][0] + u[i][1] * u[i][1] + u[i][2] * u[i][2] + u[i][3] * u[i][3]; }
;     ss = wave_sum(ss); ss2 = wave_sum(ss2); const float rs = rsqrtf(ss * (1.0f / 1024.0f) + 1e-6f), rs2 = rsqrtf(ss2 * (1.0f / 1024.0f) + 1e-6f);
;     bf16_t* q = HN + (size_t)row * DM + lane * 8; bf16_t* q2 = HN + (size_t)row2 * DM + lane * 8;
; #pragma unroll
;     for (int i = 0; i < 2; ++i) { store8bf(q + 512 * i, v[2 * i] * rs * gv[2 * i], v[2 * i + 1] * rs * gv[2 * i + 1]); store8bf(q2 + 512 * i, u[2 * i] * rs2 * gv[2 * i], u[2 * i + 1] * rs2 * gv[2 * i + 1]); }
.Ln2_lastA_first:
	s_waitcnt vmcnt(0)
	v_mul_f32_e32 v58, v18, v18
	v_fmac_f32_e32 v58, v19, v19
	v_fmac_f32_e32 v58, v20, v20
	v_fmac_f32_e32 v58, v21, v21
	v_fmac_f32_e32 v58, v22, v22
	v_fmac_f32_e32 v58, v23, v23
	v_fmac_f32_e32 v58, v24, v24
	v_fmac_f32_e32 v58, v25, v25
	v_fmac_f32_e32 v58, v26, v26
	v_fmac_f32_e32 v58, v27, v27
	v_fmac_f32_e32 v58, v28, v28
	v_fmac_f32_e32 v58, v29, v29
	v_fmac_f32_e32 v58, v30, v30
	v_fmac_f32_e32 v58, v31, v31
	v_fmac_f32_e32 v58, v32, v32
	v_fmac_f32_e32 v58, v33, v33
	v_mul_f32_e32 v59, v34, v34
	v_fmac_f32_e32 v59, v35, v35
	v_fmac_f32_e32 v59, v36, v36
	v_fmac_f32_e32 v59, v37, v37
	v_fmac_f32_e32 v59, v38, v38
	v_fmac_f32_e32 v59, v39, v39
	v_fmac_f32_e32 v59, v40, v40
	v_fmac_f32_e32 v59, v41, v41
	v_fmac_f32_e32 v59, v42, v42
	v_fmac_f32_e32 v59, v43, v43
	v_fmac_f32_e32 v59, v44, v44
	v_fmac_f32_e32 v59, v45, v45
	v_fmac_f32_e32 v59, v46, v46
	v_fmac_f32_e32 v59, v47, v47
	v_fmac_f32_e32 v59, v48, v48
	v_fmac_f32_e32 v59, v49, v49
	v_lshlrev_b32_e32 v68, 2, v210
	v_xor_b32_e32 v68, 0x80, v68
	ds_swizzle_b32 v61, v59 offset:swizzle(SWAP,16)
	ds_swizzle_b32 v60, v58 offset:swizzle(SWAP,16)
	s_waitcnt lgkmcnt(0)
	v_pk_add_f32 v[58:59], v[58:59], v[60:61]
	ds_swizzle_b32 v61, v59 offset:swizzle(SWAP,8)
	ds_swizzle_b32 v60, v58 offset:swizzle(SWAP,8)
	s_waitcnt lgkmcnt(0)
	v_pk_add_f32 v[58:59], v[58:59], v[60:61]
	ds_swizzle_b32 v61, v59 offset:swizzle(SWAP,4)
	ds_swizzle_b32 v60, v58 offset:swizzle(SWAP,4)
	s_waitcnt lgkmcnt(0)
	v_pk_add_f32 v[58:59], v[58:59], v[60:61]
	ds_swizzle_b32 v61, v59 offset:swizzle(SWAP,2)
	ds_swizzle_b32 v60, v58 offset:swizzle(SWAP,2)
	s_waitcnt lgkmcnt(0)
	v_pk_add_f32 v[58:59], v[58:59], v[60:61]
	ds_swizzle_b32 v61, v59 offset:swizzle(SWAP,1)
	ds_swizzle_b32 v60, v58 offset:swizzle(SWAP,1)
	s_waitcnt lgkmcnt(0)
	v_pk_add_f32 v[58:59], v[58:59], v[60:61]
	ds_bpermute_b32 v61, v68, v59
	ds_bpermute_b32 v60, v68, v58
	s_waitcnt lgkmcnt(0)
	v_pk_add_f32 v[58:59], v[58:59], v[60:61]
	s_nop 0
	v_pk_fma_f32 v[58:59], v[58:59], s[58:59], v[154:155] op_sel_hi:[1,0,0]
	s_nop 0
	v_rsq_f32_e32 v58, v58
	v_rsq_f32_e32 v60, v59
	s_nop 0
	v_pk_mul_f32 v[18:19], v[18:19], v[58:59] op_sel_hi:[1,0]
	v_pk_mul_f32 v[18:19], v[2:3], v[18:19]
	v_pk_mul_f32 v[20:21], v[20:21], v[58:59] op_sel_hi:[1,0]
	v_pk_mul_f32 v[20:21], v[4:5], v[20:21]
	v_pk_mul_f32 v[22:23], v[22:23], v[58:59] op_sel_hi:[1,0]
	v_pk_mul_f32 v[22:23], v[6:7], v[22:23]
	v_pk_mul_f32 v[24:25], v[24:25], v[58:59] op_sel_hi:[1,0]
	v_pk_mul_f32 v[24:25], v[8:9], v[24:25]
	v_pk_mul_f32 v[26:27], v[26:27], v[58:59] op_sel_hi:[1,0]
	v_pk_mul_f32 v[26:27], v[10:11], v[26:27]
	v_pk_mul_f32 v[28:29], v[28:29], v[58:59] op_sel_hi:[1,0]
	v_pk_mul_f32 v[28:29], v[12:13], v[28:29]
	v_pk_mul_f32 v[30:31], v[30:31], v[58:59] op_sel_hi:[1,0]
	v_pk_mul_f32 v[30:31], v[14:15], v[30:31]
	v_pk_mul_f32 v[32:33], v[32:33], v[58:59] op_sel_hi:[1,0]
	v_pk_mul_f32 v[32:33], v[16:17], v[32:33]
	v_pk_mul_f32 v[34:35], v[34:35], v[60:61] op_sel_hi:[1,0]
	v_pk_mul_f32 v[34:35], v[2:3], v[34:35]
	v_pk_mul_f32 v[36:37], v[36:37], v[60:61] op_sel_hi:[1,0]
	v_pk_mul_f32 v[36:37], v[4:5], v[36:37]
	v_pk_mul_f32 v[38:39], v[38:39], v[60:61] op_sel_hi:[1,0]
	v_pk_mul_f32 v[38:39], v[6:7], v[38:39]
	v_pk_mul_f32 v[40:41], v[40:41], v[60:61] op_sel_hi:[1,0]
	v_pk_mul_f32 v[40:41], v[8:9], v[40:41]
	v_pk_mul_f32 v[42:43], v[42:43], v[60:61] op_sel_hi:[1,0]
	v_pk_mul_f32 v[42:43], v[10:11], v[42:43]
	v_pk_mul_f32 v[44:45], v[44:45], v[60:61] op_sel_hi:[1,0]
	v_pk_mul_f32 v[44:45], v[12:13], v[44:45]
	v_pk_mul_f32 v[46:47], v[46:47], v[60:61] op_sel_hi:[1,0]
	v_pk_mul_f32 v[46:47], v[14:15], v[46:47]
	v_pk_mul_f32 v[48:49], v[48:49], v[60:61] op_sel_hi:[1,0]
	v_pk_mul_f32 v[48:49], v[16:17], v[48:49]
	v_cvt_pk_bf16_f32 v18, v18, v19
	v_cvt_pk_bf16_f32 v19, v20, v21
	v_cvt_pk_bf16_f32 v22, v22, v23
	v_cvt_pk_bf16_f32 v23, v24, v25
	v_cvt_pk_bf16_f32 v26, v26, v27
	v_cvt_pk_bf16_f32 v27, v28, v29
	v_cvt_pk_bf16_f32 v30, v30, v31
	v_cvt_pk_bf16_f32 v31, v32, v33
	global_store_dwordx2 v[54:55], v[18:19], off sc1
	global_store_dwordx2 v[54:55], v[22:23], off offset:512 sc1
	global_store_dwordx2 v[54:55], v[26:27], off offset:1024 sc1
	global_store_dwordx2 v[54:55], v[30:31], off offset:1536 sc1
	v_cvt_pk_bf16_f32 v34, v34, v35
	v_cvt_pk_bf16_f32 v35, v36, v37
	v_cvt_pk_bf16_f32 v38, v38, v39
	v_cvt_pk_bf16_f32 v39, v40, v41
	v_cvt_pk_bf16_f32 v42, v42, v43
	v_cvt_pk_bf16_f32 v43, v44, v45
	v_cvt_pk_bf16_f32 v46, v46, v47
	v_cvt_pk_bf16_f32 v47, v48, v49
	global_store_dwordx2 v[56:57], v[34:35], off sc1
	global_store_dwordx2 v[56:57], v[38:39], off offset:512 sc1
	global_store_dwordx2 v[56:57], v[42:43], off offset:1024 sc1
	global_store_dwordx2 v[56:57], v[46:47], off offset:1536 sc1
	s_branch .Ln2_done
; __device__ __forceinline__ void store8bf(bf16_t* p, f32x4 v0, f32x4 v1) { u32x4 w; w.x = cvt_pk_bf16(v0[0], v0[1]); w.y = cvt_pk_bf16(v0[2], v0[3]); w.z = cvt_pk_bf16(v1[0], v1[1]); w.w = cvt_pk_bf16(v1[2], v1[3]); *(u32x4*)p = w; }
; __device__ __forceinline__ void norm_phase(const float* H, const float* g, bf16_t* HN) {
;     ...
;     const float* p = H + (size_t)row * DM + lane * 8; const float* p2 = H + (size_t)row2 * DM + lane * 8; f32x4 v[4], u[4]; float ss = 0.f, ss2 = 0.f;
; #pragma unroll
;     for (int i = 0; i < 4; ++i) { v[i] = *(const f32x4*)(p + 512 * (i >> 1) + 4 * (i & 1)); u[i] = *(const f32x4*)(p2 + 512 * (i >> 1) + 4 * (i & 1)); }
; #pragma unroll
;     for (int i = 0; i < 4; ++i) { ss += v[i][0] * v[i][0] + v[i][1] * v[i][1] + v[i][2] * v[i][2] + v[i][3] * v[i][3]; ss2 += u[i][0] * u[i][0] + u[i][1] * u[i][1] + u[i][2] * u[i][2] + u[i][3] * u[i][3]; }
;     ss = wave_sum(ss); ss2 = wave_sum(ss2); const float rs = rsqrtf(ss * (1.0f / 1024.0f) + 1e-6f), rs2 = rsqrtf(ss2 * (1.0f / 1024.0f) + 1e-6f);
;     bf16_t* q = HN + (size_t)row * DM + lane * 8; bf16_t* q2 = HN + (size_t)row2 * DM + lane * 8;
; #pragma unroll
;     for (int i = 0; i < 2; ++i) { store8bf(q + 512 * i, v[2 * i] * rs * gv[2 * i], v[2 * i + 1] * rs * gv[2 * i + 1]); store8bf(q2 + 512 * i, u[2 * i] * rs2 * gv[2 * i], u[2 * i + 1] * rs2 * gv[2 * i + 1]); }
.Ln2_lastB:
	s_waitcnt vmcnt(0)
	v_mul_f32_e32 v58, v70, v70
	v_fmac_f32_e32 v58, v71, v71
	v_fmac_f32_e32 v58, v72, v72
	v_fmac_f32_e32 v58, v73, v73
	v_fmac_f32_e32 v58, v74, v74
	v_fmac_f32_e32 v58, v75, v75
	v_fmac_f32_e32 v58, v76, v76
	v_fmac_f32_e32 v58, v77, v77
	v_fmac_f32_e32 v58, v78, v78
	v_fmac_f32_e32 v58, v79, v79
	v_fmac_f32_e32 v58, v80, v80
	v_fmac_f32_e32 v58, v81, v81
	v_fmac_f32_e32 v58, v82, v82
	v_fmac_f32_e32 v58, v83, v83
	v_fmac_f32_e32 v58, v84, v84
	v_fmac_f32_e32 v58, v85, v85
	v_mul_f32_e32 v59, v88, v88
	v_fmac_f32_e32 v59, v89, v89
	v_fmac_f32_e32 v59, v90, v90
	v_fmac_f32_e32 v59, v91, v91
	v_fmac_f32_e32 v59, v92, v92
	v_fmac_f32_e32 v59, v93, v93
	v_fmac_f32_e32 v59, v94, v94
	v_fmac_f32_e32 v59, v95, v95
	v_fmac_f32_e32 v59, v96, v96
	v_fmac_f32_e32 v59, v97, v97
	v_fmac_f32_e32 v59, v98, v98
	v_fmac_f32_e32 v59, v99, v99
	v_fmac_f32_e32 v59, v100, v100
	v_fmac_f32_e32 v59, v101, v101
	v_fmac_f32_e32 v59, v102, v102
	v_fmac_f32_e32 v59, v103, v103
	v_lshlrev_b32_e32 v68, 2, v210
	v_xor_b32_e32 v68, 0x80, v68
	ds_swizzle_b32 v61, v59 offset:swizzle(SWAP,16)
	ds_swizzle_b32 v60, v58 offset:swizzle(SWAP,16)
	s_waitcnt lgkmcnt(0)
	v_pk_add_f32 v[58:59], v[58:59], v[60:61]
	ds_swizzle_b32 v61, v59 offset:swizzle(SWAP,8)
	ds_swizzle_b32 v60, v58 offset:swizzle(SWAP,8)
	s_waitcnt lgkmcnt(0)
	v_pk_add_f32 v[58:59], v[58:59], v[60:61]
	ds_swizzle_b32 v61, v59 offset:swizzle(SWAP,4)
	ds_swizzle_b32 v60, v58 offset:swizzle(SWAP,4)
	s_waitcnt lgkmcnt(0)
	v_pk_add_f32 v[58:59], v[58:59], v[60:61]
	ds_swizzle_b32 v61, v59 offset:swizzle(SWAP,2)
	ds_swizzle_b32 v60, v58 offset:swizzle(SWAP,2)
	s_waitcnt lgkmcnt(0)
	v_pk_add_f32 v[58:59], v[58:59], v[60:61]
	ds_swizzle_b32 v61, v59 offset:swizzle(SWAP,1)
	ds_swizzle_b32 v60, v58 offset:swizzle(SWAP,1)
	s_waitcnt lgkmcnt(0)
	v_pk_add_f32 v[58:59], v[58:59], v[60:61]
	ds_bpermute_b32 v61, v68, v59
	ds_bpermute_b32 v60, v68, v58
	s_waitcnt lgkmcnt(0)
	v_pk_add_f32 v[58:59], v[58:59], v[60:61]
	s_nop 0
	v_pk_fma_f32 v[58:59], v[58:59], s[58:59], v[154:155] op_sel_hi:[1,0,0]
	s_nop 0
	v_rsq_f32_e32 v58, v58
	v_rsq_f32_e32 v60, v59
	s_nop 0
	v_pk_mul_f32 v[70:71], v[70:71], v[58:59] op_sel_hi:[1,0]
	v_pk_mul_f32 v[70:71], v[2:3], v[70:71]
	v_pk_mul_f32 v[72:73], v[72:73], v[58:59] op_sel_hi:[1,0]
	v_pk_mul_f32 v[72:73], v[4:5], v[72:73]
	v_pk_mul_f32 v[74:75], v[74:75], v[58:59] op_sel_hi:[1,0]
	v_pk_mul_f32 v[74:75], v[6:7], v[74:75]
	v_pk_mul_f32 v[76:77], v[76:77], v[58:59] op_sel_hi:[1,0]
	v_pk_mul_f32 v[76:77], v[8:9], v[76:77]
	v_pk_mul_f32 v[78:79], v[78:79], v[58:59] op_sel_hi:[1,0]
	v_pk_mul_f32 v[78:79], v[10:11], v[78:79]
	v_pk_mul_f32 v[80:81], v[80:81], v[58:59] op_sel_hi:[1,0]
	v_pk_mul_f32 v[80:81], v[12:13], v[80:81]
	v_pk_mul_f32 v[82:83], v[82:83], v[58:59] op_sel_hi:[1,0]
	v_pk_mul_f32 v[82:83], v[14:15], v[82:83]
	v_pk_mul_f32 v[84:85], v[84:85], v[58:59] op_sel_hi:[1,0]
	v_pk_mul_f32 v[84:85], v[16:17], v[84:85]
	v_pk_mul_f32 v[88:89], v[88:89], v[60:61] op_sel_hi:[1,0]
	v_pk_mul_f32 v[88:89], v[2:3], v[88:89]
	v_pk_mul_f32 v[90:91], v[90:91], v[60:61] op_sel_hi:[1,0]
	v_pk_mul_f32 v[90:91], v[4:5], v[90:91]
	v_pk_mul_f32 v[92:93], v[92:93], v[60:61] op_sel_hi:[1,0]
	v_pk_mul_f32 v[92:93], v[6:7], v[92:93]
	v_pk_mul_f32 v[94:95], v[94:95], v[60:61] op_sel_hi:[1,0]
	v_pk_mul_f32 v[94:95], v[8:9], v[94:95]
	v_pk_mul_f32 v[96:97], v[96:97], v[60:61] op_sel_hi:[1,0]
	v_pk_mul_f32 v[96:97], v[10:11], v[96:97]
	v_pk_mul_f32 v[98:99], v[98:99], v[60:61] op_sel_hi:[1,0]
	v_pk_mul_f32 v[98:99], v[12:13], v[98:99]
	v_pk_mul_f32 v[100:101], v[100:101], v[60:61] op_sel_hi:[1,0]
	v_pk_mul_f32 v[100:101], v[14:15], v[100:101]
	v_pk_mul_f32 v[102:103], v[102:103], v[60:61] op_sel_hi:[1,0]
	v_pk_mul_f32 v[102:103], v[16:17], v[102:103]
	v_cvt_pk_bf16_f32 v70, v70, v71
	v_cvt_pk_bf16_f32 v71, v72, v73
	v_cvt_pk_bf16_f32 v74, v74, v75
	v_cvt_pk_bf16_f32 v75, v76, v77
	v_cvt_pk_bf16_f32 v78, v78, v79
	v_cvt_pk_bf16_f32 v79, v80, v81
	v_cvt_pk_bf16_f32 v82, v82, v83
	v_cvt_pk_bf16_f32 v83, v84, v85
	global_store_dwordx2 v[128:129], v[70:71], off sc1
	global_store_dwordx2 v[128:129], v[74:75], off offset:512 sc1
	global_store_dwordx2 v[128:129], v[78:79], off offset:1024 sc1
	global_store_dwordx2 v[128:129], v[82:83], off offset:1536 sc1
	v_cvt_pk_bf16_f32 v88, v88, v89
	v_cvt_pk_bf16_f32 v89, v90, v91
	v_cvt_pk_bf16_f32 v92, v92, v93
	v_cvt_pk_bf16_f32 v93, v94, v95
	v_cvt_pk_bf16_f32 v96, v96, v97
	v_cvt_pk_bf16_f32 v97, v98, v99
	v_cvt_pk_bf16_f32 v100, v100, v101
	v_cvt_pk_bf16_f32 v101, v102, v103
	global_store_dwordx2 v[130:131], v[88:89], off sc1
	global_store_dwordx2 v[130:131], v[92:93], off offset:512 sc1
	global_store_dwordx2 v[130:131], v[96:97], off offset:1024 sc1
	global_store_dwordx2 v[130:131], v[100:101], off offset:1536 sc1
	s_branch .Ln2_done
; __device__ __forceinline__ void store8bf(bf16_t* p, f32x4 v0, f32x4 v1) { u32x4 w; w.x = cvt_pk_bf16(v0[0], v0[1]); w.y = cvt_pk_bf16(v0[2], v0[3]); w.z = cvt_pk_bf16(v1[0], v1[1]); w.w = cvt_pk_bf16(v1[2], v1[3]); *(u32x4*)p = w; }
; __device__ __forceinline__ void norm_phase(const float* H, const float* g, bf16_t* HN) {
;     ...
;     const float* p = H + (size_t)row * DM + lane * 8; const float* p2 = H + (size_t)row2 * DM + lane * 8; f32x4 v[4], u[4]; float ss = 0.f, ss2 = 0.f;
; #pragma unroll
;     for (int i = 0; i < 4; ++i) { v[i] = *(const f32x4*)(p + 512 * (i >> 1) + 4 * (i & 1)); u[i] = *(const f32x4*)(p2 + 512 * (i >> 1) + 4 * (i & 1)); }
; #pragma unroll
;     for (int i = 0; i < 4; ++i) { ss += v[i][0] * v[i][0] + v[i][1] * v[i][1] + v[i][2] * v[i][2] + v[i][3] * v[i][3]; ss2 += u[i][0] * u[i][0] + u[i][1] * u[i][1] + u[i][2] * u[i][2] + u[i][3] * u[i][3]; }
;     ss = wave_sum(ss); ss2 = wave_sum(ss2); const float rs = rsqrtf(ss * (1.0f / 1024.0f) + 1e-6f), rs2 = rsqrtf(ss2 * (1.0f / 1024.0f) + 1e-6f);
;     bf16_t* q = HN + (size_t)row * DM + lane * 8; bf16_t* q2 = HN + (size_t)row2 * DM + lane * 8;
; #pragma unroll
;     for (int i = 0; i < 2; ++i) { store8bf(q + 512 * i, v[2 * i] * rs * gv[2 * i], v[2 * i + 1] * rs * gv[2 * i + 1]); store8bf(q2 + 512 * i, u[2 * i] * rs2 * gv[2 * i], u[2 * i + 1] * rs2 * gv[2 * i + 1]); }
.Ln2_lastA:
	s_waitcnt vmcnt(0)
	v_mul_f32_e32 v58, v18, v18
	v_fmac_f32_e32 v58, v19, v19
	v_fmac_f32_e32 v58, v20, v20
	v_fmac_f32_e32 v58, v21, v21
	v_fmac_f32_e32 v58, v22, v22
	v_fmac_f32_e32 v58, v23, v23
	v_fmac_f32_e32 v58, v24, v24
	v_fmac_f32_e32 v58, v25, v25
	v_fmac_f32_e32 v58, v26, v26
	v_fmac_f32_e32 v58, v27, v27
	v_fmac_f32_e32 v58, v28, v28
	v_fmac_f32_e32 v58, v29, v29
	v_fmac_f32_e32 v58, v30, v30
	v_fmac_f32_e32 v58, v31, v31
	v_fmac_f32_e32 v58, v32, v32
	v_fmac_f32_e32 v58, v33, v33
	v_mul_f32_e32 v59, v34, v34
	v_fmac_f32_e32 v59, v35, v35
	v_fmac_f32_e32 v59, v36, v36
	v_fmac_f32_e32 v59, v37, v37
	v_fmac_f32_e32 v59, v38, v38
	v_fmac_f32_e32 v59, v39, v39
	v_fmac_f32_e32 v59, v40, v40
	v_fmac_f32_e32 v59, v41, v41
	v_fmac_f32_e32 v59, v42, v42
	v_fmac_f32_e32 v59, v43, v43
	v_fmac_f32_e32 v59, v44, v44
	v_fmac_f32_e32 v59, v45, v45
	v_fmac_f32_e32 v59, v46, v46
	v_fmac_f32_e32 v59, v47, v47
	v_fmac_f32_e32 v59, v48, v48
	v_fmac_f32_e32 v59, v49, v49
	v_lshlrev_b32_e32 v68, 2, v210
	v_xor_b32_e32 v68, 0x80, v68
	ds_swizzle_b32 v61, v59 offset:swizzle(SWAP,16)
	ds_swizzle_b32 v60, v58 offset:swizzle(SWAP,16)
	s_waitcnt lgkmcnt(0)
	v_pk_add_f32 v[58:59], v[58:59], v[60:61]
	ds_swizzle_b32 v61, v59 offset:swizzle(SWAP,8)
	ds_swizzle_b32 v60, v58 offset:swizzle(SWAP,8)
	s_waitcnt lgkmcnt(0)
	v_pk_add_f32 v[58:59], v[58:59], v[60:61]
	ds_swizzle_b32 v61, v59 offset:swizzle(SWAP,4)
	ds_swizzle_b32 v60, v58 offset:swizzle(SWAP,4)
	s_waitcnt lgkmcnt(0)
	v_pk_add_f32 v[58:59], v[58:59], v[60:61]
	ds_swizzle_b32 v61, v59 offset:swizzle(SWAP,2)
	ds_swizzle_b32 v60, v58 offset:swizzle(SWAP,2)
	s_waitcnt lgkmcnt(0)
	v_pk_add_f32 v[58:59], v[58:59], v[60:61]
	ds_swizzle_b32 v61, v59 offset:swizzle(SWAP,1)
	ds_swizzle_b32 v60, v58 offset:swizzle(SWAP,1)
	s_waitcnt lgkmcnt(0)
	v_pk_add_f32 v[58:59], v[58:59], v[60:61]
	ds_bpermute_b32 v61, v68, v59
	ds_bpermute_b32 v60, v68, v58
	s_waitcnt lgkmcnt(0)
	v_pk_add_f32 v[58:59], v[58:59], v[60:61]
	s_nop 0
	v_pk_fma_f32 v[58:59], v[58:59], s[58:59], v[154:155] op_sel_hi:[1,0,0]
	s_nop 0
	v_rsq_f32_e32 v58, v58
	v_rsq_f32_e32 v60, v59
	s_nop 0
	v_pk_mul_f32 v[18:19], v[18:19], v[58:59] op_sel_hi:[1,0]
	v_pk_mul_f32 v[18:19], v[2:3], v[18:19]
	v_pk_mul_f32 v[20:21], v[20:21], v[58:59] op_sel_hi:[1,0]
	v_pk_mul_f32 v[20:21], v[4:5], v[20:21]
	v_pk_mul_f32 v[22:23], v[22:23], v[58:59] op_sel_hi:[1,0]
	v_pk_mul_f32 v[22:23], v[6:7], v[22:23]
	v_pk_mul_f32 v[24:25], v[24:25], v[58:59] op_sel_hi:[1,0]
	v_pk_mul_f32 v[24:25], v[8:9], v[24:25]
	v_pk_mul_f32 v[26:27], v[26:27], v[58:59] op_sel_hi:[1,0]
	v_pk_mul_f32 v[26:27], v[10:11], v[26:27]
	v_pk_mul_f32 v[28:29], v[28:29], v[58:59] op_sel_hi:[1,0]
	v_pk_mul_f32 v[28:29], v[12:13], v[28:29]
	v_pk_mul_f32 v[30:31], v[30:31], v[58:59] op_sel_hi:[1,0]
	v_pk_mul_f32 v[30:31], v[14:15], v[30:31]
	v_pk_mul_f32 v[32:33], v[32:33], v[58:59] op_sel_hi:[1,0]
	v_pk_mul_f32 v[32:33], v[16:17], v[32:33]
	v_pk_mul_f32 v[34:35], v[34:35], v[60:61] op_sel_hi:[1,0]
	v_pk_mul_f32 v[34:35], v[2:3], v[34:35]
	v_pk_mul_f32 v[36:37], v[36:37], v[60:61] op_sel_hi:[1,0]
	v_pk_mul_f32 v[36:37], v[4:5], v[36:37]
	v_pk_mul_f32 v[38:39], v[38:39], v[60:61] op_sel_hi:[1,0]
	v_pk_mul_f32 v[38:39], v[6:7], v[38:39]
	v_pk_mul_f32 v[40:41], v[40:41], v[60:61] op_sel_hi:[1,0]
	v_pk_mul_f32 v[40:41], v[8:9], v[40:41]
	v_pk_mul_f32 v[42:43], v[42:43], v[60:61] op_sel_hi:[1,0]
	v_pk_mul_f32 v[42:43], v[10:11], v[42:43]
	v_pk_mul_f32 v[44:45], v[44:45], v[60:61] op_sel_hi:[1,0]
	v_pk_mul_f32 v[44:45], v[12:13], v[44:45]
	v_pk_mul_f32 v[46:47], v[46:47], v[60:61] op_sel_hi:[1,0]
	v_pk_mul_f32 v[46:47], v[14:15], v[46:47]
	v_pk_mul_f32 v[48:49], v[48:49], v[60:61] op_sel_hi:[1,0]
	v_pk_mul_f32 v[48:49], v[16:17], v[48:49]
	v_cvt_pk_bf16_f32 v18, v18, v19
	v_cvt_pk_bf16_f32 v19, v20, v21
	v_cvt_pk_bf16_f32 v22, v22, v23
	v_cvt_pk_bf16_f32 v23, v24, v25
	v_cvt_pk_bf16_f32 v26, v26, v27
	v_cvt_pk_bf16_f32 v27, v28, v29
	v_cvt_pk_bf16_f32 v30, v30, v31
	v_cvt_pk_bf16_f32 v31, v32, v33
	global_store_dwordx2 v[54:55], v[18:19], off sc1
	global_store_dwordx2 v[54:55], v[22:23], off offset:512 sc1
	global_store_dwordx2 v[54:55], v[26:27], off offset:1024 sc1
	global_store_dwordx2 v[54:55], v[30:31], off offset:1536 sc1
	v_cvt_pk_bf16_f32 v34, v34, v35
	v_cvt_pk_bf16_f32 v35, v36, v37
	v_cvt_pk_bf16_f32 v38, v38, v39
	v_cvt_pk_bf16_f32 v39, v40, v41
	v_cvt_pk_bf16_f32 v42, v42, v43
	v_cvt_pk_bf16_f32 v43, v44, v45
	v_cvt_pk_bf16_f32 v46, v46, v47
	v_cvt_pk_bf16_f32 v47, v48, v49
	global_store_dwordx2 v[56:57], v[34:35], off sc1
	global_store_dwordx2 v[56:57], v[38:39], off offset:512 sc1
	global_store_dwordx2 v[56:57], v[42:43], off offset:1024 sc1
	global_store_dwordx2 v[56:57], v[46:47], off offset:1536 sc1
